# v34 + K-loops: mid-segment setprio 0/1 flips deleted and setprio 0 moved behind the closing barrier (computing wave arrives one issue slot earlier)
# speedup vs baseline: 1.0102x; 1.0021x over previous
.LBB0_246:
	s_add_u32 s3, s34, 0xfff80080
	s_addc_u32 s6, s35, -1
	s_add_i32 s7, 0, 0x10000
	s_cmp_eq_u32 s2, 28
	s_cselect_b32 s43, s15, s6
	s_cselect_b32 s42, s47, s3
	s_cselect_b32 s39, s13, s50
	s_cselect_b32 s38, s48, s49
	s_add_i32 s3, 0, 0x14000
	v_add_u32_e32 v156, s7, v145
	v_add_u32_e32 v172, s3, v145
	ds_read_b128 v[140:143], v156
	ds_read_b128 v[148:151], v156 offset:1024
	ds_read_b128 v[152:155], v156 offset:2048
	ds_read_b128 v[156:159], v156 offset:3072
	ds_read_b128 v[160:163], v172
	ds_read_b128 v[164:167], v172 offset:1024
	ds_read_b128 v[168:171], v172 offset:2048
	ds_read_b128 v[172:175], v172 offset:3072
	v_lshl_add_u64 v[176:177], s[34:35], 0, v[136:137]
	s_add_i32 m0, s18, 0xc000
	ds_read_b128 v[182:185], v147
	ds_read_b128 v[186:189], v147 offset:1024
	ds_read_b128 v[190:193], v147 offset:2048
	ds_read_b128 v[214:217], v147 offset:3072
	ds_read_b128 v[218:221], v147 offset:4096
	ds_read_b128 v[222:225], v147 offset:5120
	ds_read_b128 v[226:229], v147 offset:6144
	ds_read_b128 v[230:233], v147 offset:7168
	global_load_lds_dwordx4 v[176:177], off
	v_lshl_add_u64 v[176:177], s[34:35], 0, v[138:139]
	s_add_i32 m0, s18, 0xe000
	s_nop 0
	global_load_lds_dwordx4 v[176:177], off
	s_setprio 1
	s_waitcnt vmcnt(8)
	s_waitcnt lgkmcnt(0)
	s_barrier
	v_mfma_f32_16x16x32_bf16 v[126:129], v[140:143], v[182:185], v[126:129]
	v_mfma_f32_16x16x32_bf16 v[122:125], v[152:155], v[182:185], v[122:125]
	v_mfma_f32_16x16x32_bf16 v[118:121], v[140:143], v[190:193], v[118:121]
	v_mfma_f32_16x16x32_bf16 v[110:113], v[152:155], v[190:193], v[110:113]
	v_mfma_f32_16x16x32_bf16 v[102:105], v[140:143], v[218:221], v[102:105]
	v_mfma_f32_16x16x32_bf16 v[92:95], v[152:155], v[218:221], v[92:95]
	v_mfma_f32_16x16x32_bf16 v[84:87], v[140:143], v[226:229], v[84:87]
	v_mfma_f32_16x16x32_bf16 v[76:79], v[152:155], v[226:229], v[76:79]
	v_mfma_f32_16x16x32_bf16 v[126:129], v[148:151], v[186:189], v[126:129]
	v_mfma_f32_16x16x32_bf16 v[122:125], v[156:159], v[186:189], v[122:125]
	v_mfma_f32_16x16x32_bf16 v[118:121], v[148:151], v[214:217], v[118:121]
	v_mfma_f32_16x16x32_bf16 v[110:113], v[156:159], v[214:217], v[110:113]
	v_mfma_f32_16x16x32_bf16 v[102:105], v[148:151], v[222:225], v[102:105]
	v_mfma_f32_16x16x32_bf16 v[92:95], v[156:159], v[222:225], v[92:95]
	v_mfma_f32_16x16x32_bf16 v[84:87], v[148:151], v[230:233], v[84:87]
	v_mfma_f32_16x16x32_bf16 v[76:79], v[156:159], v[230:233], v[76:79]
	v_mfma_f32_16x16x32_bf16 v[114:117], v[160:163], v[182:185], v[114:117]
	v_mfma_f32_16x16x32_bf16 v[106:109], v[168:171], v[182:185], v[106:109]
	v_mfma_f32_16x16x32_bf16 v[98:101], v[160:163], v[190:193], v[98:101]
	v_mfma_f32_16x16x32_bf16 v[88:91], v[168:171], v[190:193], v[88:91]
	v_mfma_f32_16x16x32_bf16 v[80:83], v[160:163], v[218:221], v[80:83]
	v_mfma_f32_16x16x32_bf16 v[72:75], v[168:171], v[218:221], v[72:75]
	v_mfma_f32_16x16x32_bf16 v[68:71], v[160:163], v[226:229], v[68:71]
	v_mfma_f32_16x16x32_bf16 v[64:67], v[168:171], v[226:229], v[64:67]
	v_mfma_f32_16x16x32_bf16 v[114:117], v[164:167], v[186:189], v[114:117]
	v_mfma_f32_16x16x32_bf16 v[106:109], v[172:175], v[186:189], v[106:109]
	v_mfma_f32_16x16x32_bf16 v[98:101], v[164:167], v[214:217], v[98:101]
	v_mfma_f32_16x16x32_bf16 v[88:91], v[172:175], v[214:217], v[88:91]
	v_mfma_f32_16x16x32_bf16 v[80:83], v[164:167], v[222:225], v[80:83]
	v_mfma_f32_16x16x32_bf16 v[72:75], v[172:175], v[222:225], v[72:75]
	v_mfma_f32_16x16x32_bf16 v[68:71], v[164:167], v[230:233], v[68:71]
	v_mfma_f32_16x16x32_bf16 v[64:67], v[172:175], v[230:233], v[64:67]
	s_barrier
	s_setprio 0
	s_add_i32 s6, s7, s17
	v_lshl_add_u64 v[176:177], s[38:39], 0, v[96:97]
	s_mov_b32 m0, s6
	ds_read_b128 v[182:185], v147 offset:16384
	ds_read_b128 v[186:189], v147 offset:17408
	ds_read_b128 v[190:193], v147 offset:18432
	ds_read_b128 v[214:217], v147 offset:19456
	ds_read_b128 v[218:221], v147 offset:20480
	ds_read_b128 v[222:225], v147 offset:21504
	ds_read_b128 v[226:229], v147 offset:22528
	ds_read_b128 v[230:233], v147 offset:23552
	global_load_lds_dwordx4 v[176:177], off
	s_add_i32 m0, s6, 0x2000
	s_add_u32 s6, s38, 0x80000
	v_lshl_add_u64 v[178:179], s[38:39], 0, v[130:131]
	s_addc_u32 s7, s39, 0
	s_add_i32 s3, s3, s17
	global_load_lds_dwordx4 v[178:179], off
	v_lshl_add_u64 v[180:181], s[6:7], 0, v[96:97]
	s_mov_b32 m0, s3
	v_lshl_add_u64 v[194:195], s[42:43], 0, v[132:133]
	global_load_lds_dwordx4 v[180:181], off
	v_lshl_add_u64 v[180:181], s[6:7], 0, v[130:131]
	s_add_i32 m0, s3, 0x2000
	s_nop 0
	global_load_lds_dwordx4 v[180:181], off
	v_lshl_add_u64 v[180:181], s[42:43], 0, v[134:135]
	s_mov_b32 m0, s18
	s_nop 0
	global_load_lds_dwordx4 v[180:181], off
	s_mov_b32 m0, s19
	s_nop 0
	global_load_lds_dwordx4 v[194:195], off
	s_setprio 1
	s_waitcnt vmcnt(8)
	s_waitcnt lgkmcnt(0)
	s_barrier
	v_mfma_f32_16x16x32_bf16 v[60:63], v[140:143], v[182:185], v[60:63]
	v_mfma_f32_16x16x32_bf16 v[56:59], v[152:155], v[182:185], v[56:59]
	v_mfma_f32_16x16x32_bf16 v[52:55], v[140:143], v[190:193], v[52:55]
	v_mfma_f32_16x16x32_bf16 v[44:47], v[152:155], v[190:193], v[44:47]
	v_mfma_f32_16x16x32_bf16 v[36:39], v[140:143], v[218:221], v[36:39]
	v_mfma_f32_16x16x32_bf16 v[28:31], v[152:155], v[218:221], v[28:31]
	v_mfma_f32_16x16x32_bf16 v[20:23], v[140:143], v[226:229], v[20:23]
	v_mfma_f32_16x16x32_bf16 v[12:15], v[152:155], v[226:229], v[12:15]
	v_mfma_f32_16x16x32_bf16 v[60:63], v[148:151], v[186:189], v[60:63]
	v_mfma_f32_16x16x32_bf16 v[56:59], v[156:159], v[186:189], v[56:59]
	v_mfma_f32_16x16x32_bf16 v[52:55], v[148:151], v[214:217], v[52:55]
	v_mfma_f32_16x16x32_bf16 v[44:47], v[156:159], v[214:217], v[44:47]
	v_mfma_f32_16x16x32_bf16 v[36:39], v[148:151], v[222:225], v[36:39]
	v_mfma_f32_16x16x32_bf16 v[28:31], v[156:159], v[222:225], v[28:31]
	v_mfma_f32_16x16x32_bf16 v[20:23], v[148:151], v[230:233], v[20:23]
	v_mfma_f32_16x16x32_bf16 v[12:15], v[156:159], v[230:233], v[12:15]
	v_mfma_f32_16x16x32_bf16 v[48:51], v[160:163], v[182:185], v[48:51]
	v_mfma_f32_16x16x32_bf16 v[40:43], v[168:171], v[182:185], v[40:43]
	v_mfma_f32_16x16x32_bf16 v[32:35], v[160:163], v[190:193], v[32:35]
	v_mfma_f32_16x16x32_bf16 v[24:27], v[168:171], v[190:193], v[24:27]
	v_mfma_f32_16x16x32_bf16 v[16:19], v[160:163], v[218:221], v[16:19]
	v_mfma_f32_16x16x32_bf16 v[8:11], v[168:171], v[218:221], v[8:11]
	v_mfma_f32_16x16x32_bf16 v[4:7], v[160:163], v[226:229], v[4:7]
	v_mfma_f32_16x16x32_bf16 v[0:3], v[168:171], v[226:229], v[0:3]
	v_mfma_f32_16x16x32_bf16 v[48:51], v[164:167], v[186:189], v[48:51]
	v_mfma_f32_16x16x32_bf16 v[40:43], v[172:175], v[186:189], v[40:43]
	v_mfma_f32_16x16x32_bf16 v[32:35], v[164:167], v[214:217], v[32:35]
	v_mfma_f32_16x16x32_bf16 v[24:27], v[172:175], v[214:217], v[24:27]
	v_mfma_f32_16x16x32_bf16 v[16:19], v[164:167], v[222:225], v[16:19]
	v_mfma_f32_16x16x32_bf16 v[8:11], v[172:175], v[222:225], v[8:11]
	v_mfma_f32_16x16x32_bf16 v[4:7], v[164:167], v[230:233], v[4:7]
	v_mfma_f32_16x16x32_bf16 v[0:3], v[172:175], v[230:233], v[0:3]
	s_barrier
	s_setprio 0
	s_add_i32 s3, 0, 0x18000
	s_add_i32 s51, 0, 0x1c000
	v_add_u32_e32 v156, s3, v145
	v_add_u32_e32 v172, s51, v145
	ds_read_b128 v[140:143], v156
	ds_read_b128 v[148:151], v156 offset:1024
	ds_read_b128 v[152:155], v156 offset:2048
	ds_read_b128 v[156:159], v156 offset:3072
	ds_read_b128 v[160:163], v172
	ds_read_b128 v[164:167], v172 offset:1024
	ds_read_b128 v[168:171], v172 offset:2048
	ds_read_b128 v[172:175], v172 offset:3072
	s_add_u32 s6, s42, 0x80000
	s_addc_u32 s7, s43, 0
	s_mov_b32 m0, s20
	v_lshl_add_u64 v[202:203], s[6:7], 0, v[134:135]
	ds_read_b128 v[182:185], v147 offset:32768
	ds_read_b128 v[186:189], v147 offset:33792
	ds_read_b128 v[190:193], v147 offset:34816
	ds_read_b128 v[214:217], v147 offset:35840
	ds_read_b128 v[218:221], v147 offset:36864
	ds_read_b128 v[222:225], v147 offset:37888
	ds_read_b128 v[226:229], v147 offset:38912
	ds_read_b128 v[230:233], v147 offset:39936
	global_load_lds_dwordx4 v[202:203], off
	v_lshl_add_u64 v[202:203], s[6:7], 0, v[132:133]
	s_mov_b32 m0, s36
	s_nop 0
	global_load_lds_dwordx4 v[202:203], off
	s_setprio 1
	s_waitcnt vmcnt(8)
	s_waitcnt lgkmcnt(0)
	s_barrier
	v_mfma_f32_16x16x32_bf16 v[126:129], v[140:143], v[182:185], v[126:129]
	v_mfma_f32_16x16x32_bf16 v[122:125], v[152:155], v[182:185], v[122:125]
	v_mfma_f32_16x16x32_bf16 v[118:121], v[140:143], v[190:193], v[118:121]
	v_mfma_f32_16x16x32_bf16 v[110:113], v[152:155], v[190:193], v[110:113]
	v_mfma_f32_16x16x32_bf16 v[102:105], v[140:143], v[218:221], v[102:105]
	v_mfma_f32_16x16x32_bf16 v[92:95], v[152:155], v[218:221], v[92:95]
	v_mfma_f32_16x16x32_bf16 v[84:87], v[140:143], v[226:229], v[84:87]
	v_mfma_f32_16x16x32_bf16 v[76:79], v[152:155], v[226:229], v[76:79]
	v_mfma_f32_16x16x32_bf16 v[126:129], v[148:151], v[186:189], v[126:129]
	v_mfma_f32_16x16x32_bf16 v[122:125], v[156:159], v[186:189], v[122:125]
	v_mfma_f32_16x16x32_bf16 v[118:121], v[148:151], v[214:217], v[118:121]
	v_mfma_f32_16x16x32_bf16 v[110:113], v[156:159], v[214:217], v[110:113]
	v_mfma_f32_16x16x32_bf16 v[102:105], v[148:151], v[222:225], v[102:105]
	v_mfma_f32_16x16x32_bf16 v[92:95], v[156:159], v[222:225], v[92:95]
	v_mfma_f32_16x16x32_bf16 v[84:87], v[148:151], v[230:233], v[84:87]
	v_mfma_f32_16x16x32_bf16 v[76:79], v[156:159], v[230:233], v[76:79]
	v_mfma_f32_16x16x32_bf16 v[114:117], v[160:163], v[182:185], v[114:117]
	v_mfma_f32_16x16x32_bf16 v[106:109], v[168:171], v[182:185], v[106:109]
	v_mfma_f32_16x16x32_bf16 v[98:101], v[160:163], v[190:193], v[98:101]
	v_mfma_f32_16x16x32_bf16 v[88:91], v[168:171], v[190:193], v[88:91]
	v_mfma_f32_16x16x32_bf16 v[80:83], v[160:163], v[218:221], v[80:83]
	v_mfma_f32_16x16x32_bf16 v[72:75], v[168:171], v[218:221], v[72:75]
	v_mfma_f32_16x16x32_bf16 v[68:71], v[160:163], v[226:229], v[68:71]
	v_mfma_f32_16x16x32_bf16 v[64:67], v[168:171], v[226:229], v[64:67]
	v_mfma_f32_16x16x32_bf16 v[114:117], v[164:167], v[186:189], v[114:117]
	v_mfma_f32_16x16x32_bf16 v[106:109], v[172:175], v[186:189], v[106:109]
	v_mfma_f32_16x16x32_bf16 v[98:101], v[164:167], v[214:217], v[98:101]
	v_mfma_f32_16x16x32_bf16 v[88:91], v[172:175], v[214:217], v[88:91]
	v_mfma_f32_16x16x32_bf16 v[80:83], v[164:167], v[222:225], v[80:83]
	v_mfma_f32_16x16x32_bf16 v[72:75], v[172:175], v[222:225], v[72:75]
	v_mfma_f32_16x16x32_bf16 v[68:71], v[164:167], v[230:233], v[68:71]
	v_mfma_f32_16x16x32_bf16 v[64:67], v[172:175], v[230:233], v[64:67]
	s_barrier
	s_setprio 0
	s_add_i32 s3, s3, s17
	v_lshl_add_u64 v[176:177], v[176:177], 0, s[30:31]
	s_mov_b32 m0, s3
	ds_read_b128 v[182:185], v147 offset:49152
	ds_read_b128 v[186:189], v147 offset:50176
	ds_read_b128 v[190:193], v147 offset:51200
	ds_read_b128 v[214:217], v147 offset:52224
	ds_read_b128 v[218:221], v147 offset:53248
	ds_read_b128 v[222:225], v147 offset:54272
	ds_read_b128 v[226:229], v147 offset:55296
	ds_read_b128 v[230:233], v147 offset:56320
	global_load_lds_dwordx4 v[176:177], off
	s_add_i32 m0, s3, 0x2000
	s_add_u32 s6, s38, 0x80080
	v_lshl_add_u64 v[176:177], v[178:179], 0, s[30:31]
	s_addc_u32 s7, s39, 0
	s_add_i32 s3, s51, s17
	global_load_lds_dwordx4 v[176:177], off
	v_lshl_add_u64 v[176:177], s[6:7], 0, v[96:97]
	s_mov_b32 m0, s3
	s_nop 0
	global_load_lds_dwordx4 v[176:177], off
	v_lshl_add_u64 v[176:177], s[6:7], 0, v[130:131]
	s_add_i32 m0, s3, 0x2000
	s_nop 0
	global_load_lds_dwordx4 v[176:177], off
	v_lshl_add_u64 v[176:177], v[180:181], 0, s[30:31]
	s_mov_b32 m0, s37
	s_nop 0
	global_load_lds_dwordx4 v[176:177], off
	v_lshl_add_u64 v[176:177], v[194:195], 0, s[30:31]
	s_mov_b32 m0, s40
	s_nop 0
	global_load_lds_dwordx4 v[176:177], off
	s_setprio 1
	s_waitcnt vmcnt(8)
	s_waitcnt lgkmcnt(0)
	s_barrier
	v_mfma_f32_16x16x32_bf16 v[60:63], v[140:143], v[182:185], v[60:63]
	v_mfma_f32_16x16x32_bf16 v[56:59], v[152:155], v[182:185], v[56:59]
	v_mfma_f32_16x16x32_bf16 v[52:55], v[140:143], v[190:193], v[52:55]
	v_mfma_f32_16x16x32_bf16 v[44:47], v[152:155], v[190:193], v[44:47]
	v_mfma_f32_16x16x32_bf16 v[36:39], v[140:143], v[218:221], v[36:39]
	v_mfma_f32_16x16x32_bf16 v[28:31], v[152:155], v[218:221], v[28:31]
	v_mfma_f32_16x16x32_bf16 v[20:23], v[140:143], v[226:229], v[20:23]
	v_mfma_f32_16x16x32_bf16 v[12:15], v[152:155], v[226:229], v[12:15]
	v_mfma_f32_16x16x32_bf16 v[60:63], v[148:151], v[186:189], v[60:63]
	v_mfma_f32_16x16x32_bf16 v[56:59], v[156:159], v[186:189], v[56:59]
	v_mfma_f32_16x16x32_bf16 v[52:55], v[148:151], v[214:217], v[52:55]
	v_mfma_f32_16x16x32_bf16 v[44:47], v[156:159], v[214:217], v[44:47]
	v_mfma_f32_16x16x32_bf16 v[36:39], v[148:151], v[222:225], v[36:39]
	v_mfma_f32_16x16x32_bf16 v[28:31], v[156:159], v[222:225], v[28:31]
	v_mfma_f32_16x16x32_bf16 v[20:23], v[148:151], v[230:233], v[20:23]
	v_mfma_f32_16x16x32_bf16 v[12:15], v[156:159], v[230:233], v[12:15]
	v_mfma_f32_16x16x32_bf16 v[48:51], v[160:163], v[182:185], v[48:51]
	v_mfma_f32_16x16x32_bf16 v[40:43], v[168:171], v[182:185], v[40:43]
	v_mfma_f32_16x16x32_bf16 v[32:35], v[160:163], v[190:193], v[32:35]
	v_mfma_f32_16x16x32_bf16 v[24:27], v[168:171], v[190:193], v[24:27]
	v_mfma_f32_16x16x32_bf16 v[16:19], v[160:163], v[218:221], v[16:19]
	v_mfma_f32_16x16x32_bf16 v[8:11], v[168:171], v[218:221], v[8:11]
	v_mfma_f32_16x16x32_bf16 v[4:7], v[160:163], v[226:229], v[4:7]
	v_mfma_f32_16x16x32_bf16 v[0:3], v[168:171], v[226:229], v[0:3]
	v_mfma_f32_16x16x32_bf16 v[48:51], v[164:167], v[186:189], v[48:51]
	v_mfma_f32_16x16x32_bf16 v[40:43], v[172:175], v[186:189], v[40:43]
	v_mfma_f32_16x16x32_bf16 v[32:35], v[164:167], v[214:217], v[32:35]
	v_mfma_f32_16x16x32_bf16 v[24:27], v[172:175], v[214:217], v[24:27]
	v_mfma_f32_16x16x32_bf16 v[16:19], v[164:167], v[222:225], v[16:19]
	v_mfma_f32_16x16x32_bf16 v[8:11], v[172:175], v[222:225], v[8:11]
	v_mfma_f32_16x16x32_bf16 v[4:7], v[164:167], v[230:233], v[4:7]
	v_mfma_f32_16x16x32_bf16 v[0:3], v[172:175], v[230:233], v[0:3]
	s_barrier
	s_setprio 0
	s_add_i32 s2, s2, 2
	s_add_u32 s34, s34, 0x100
	s_addc_u32 s35, s35, 0
	s_add_u32 s49, s49, 0x100
	s_addc_u32 s50, s50, 0
	s_cmp_gt_u32 s2, 29
	s_cbranch_scc0 .LBB0_246
	s_nop 0
	s_nop 0
	s_nop 0
	s_nop 0
	s_nop 0
	s_nop 0
	s_nop 0
	s_nop 0
	s_nop 0
	s_nop 0
	s_nop 0
	s_nop 0
	s_and_b64 vcc, exec, s[10:11]
	s_cbranch_vccz .LBB0_249
	s_barrier

.LBB0_421:
	s_add_u32 s3, s22, 0xfffe0080
	s_addc_u32 s6, s23, -1
	s_add_i32 s7, 0, 0x10000
	s_cmp_eq_u32 s2, 4
	s_cselect_b32 s35, s4, s6
	s_cselect_b32 s34, s5, s3
	v_add_u32_e32 v96, s7, v176
	s_cselect_b32 s25, s9, s17
	s_cselect_b32 s24, s13, s15
	s_add_i32 s3, 0, 0x14000
	ds_read_b128 v[56:59], v96
	ds_read_b128 v[60:63], v96 offset:1024
	ds_read_b128 v[138:141], v96 offset:2048
	ds_read_b128 v[142:145], v96 offset:3072
	v_add_u32_e32 v96, s3, v176
	ds_read_b128 v[146:149], v96
	ds_read_b128 v[150:153], v96 offset:1024
	ds_read_b128 v[154:157], v96 offset:2048
	ds_read_b128 v[170:173], v96 offset:3072
	v_lshl_add_u64 v[174:175], s[22:23], 0, v[166:167]
	s_add_i32 m0, s75, 0xc000
	ds_read_b128 v[182:185], v177
	ds_read_b128 v[186:189], v177 offset:1024
	ds_read_b128 v[190:193], v177 offset:2048
	ds_read_b128 v[214:217], v177 offset:3072
	ds_read_b128 v[218:221], v177 offset:4096
	ds_read_b128 v[222:225], v177 offset:5120
	ds_read_b128 v[226:229], v177 offset:6144
	ds_read_b128 v[230:233], v177 offset:7168
	global_load_lds_dwordx4 v[174:175], off
	v_lshl_add_u64 v[174:175], s[22:23], 0, v[168:169]
	s_add_i32 m0, s75, 0xe000
	s_nop 0
	global_load_lds_dwordx4 v[174:175], off
	s_setprio 1
	s_waitcnt vmcnt(8)
	s_waitcnt lgkmcnt(0)
	s_barrier
	v_mfma_f32_16x16x32_bf16 v[134:137], v[56:59], v[182:185], v[134:137]
	v_mfma_f32_16x16x32_bf16 v[130:133], v[138:141], v[182:185], v[130:133]
	v_mfma_f32_16x16x32_bf16 v[118:121], v[56:59], v[190:193], v[118:121]
	v_mfma_f32_16x16x32_bf16 v[114:117], v[138:141], v[190:193], v[114:117]
	v_mfma_f32_16x16x32_bf16 v[102:105], v[56:59], v[218:221], v[102:105]
	v_mfma_f32_16x16x32_bf16 v[98:101], v[138:141], v[218:221], v[98:101]
	v_mfma_f32_16x16x32_bf16 v[84:87], v[56:59], v[226:229], v[84:87]
	v_mfma_f32_16x16x32_bf16 v[80:83], v[138:141], v[226:229], v[80:83]
	v_mfma_f32_16x16x32_bf16 v[134:137], v[60:63], v[186:189], v[134:137]
	v_mfma_f32_16x16x32_bf16 v[130:133], v[142:145], v[186:189], v[130:133]
	v_mfma_f32_16x16x32_bf16 v[118:121], v[60:63], v[214:217], v[118:121]
	v_mfma_f32_16x16x32_bf16 v[114:117], v[142:145], v[214:217], v[114:117]
	v_mfma_f32_16x16x32_bf16 v[102:105], v[60:63], v[222:225], v[102:105]
	v_mfma_f32_16x16x32_bf16 v[98:101], v[142:145], v[222:225], v[98:101]
	v_mfma_f32_16x16x32_bf16 v[84:87], v[60:63], v[230:233], v[84:87]
	v_mfma_f32_16x16x32_bf16 v[80:83], v[142:145], v[230:233], v[80:83]
	v_mfma_f32_16x16x32_bf16 v[126:129], v[146:149], v[182:185], v[126:129]
	v_mfma_f32_16x16x32_bf16 v[122:125], v[154:157], v[182:185], v[122:125]
	v_mfma_f32_16x16x32_bf16 v[110:113], v[146:149], v[190:193], v[110:113]
	v_mfma_f32_16x16x32_bf16 v[106:109], v[154:157], v[190:193], v[106:109]
	v_mfma_f32_16x16x32_bf16 v[92:95], v[146:149], v[218:221], v[92:95]
	v_mfma_f32_16x16x32_bf16 v[88:91], v[154:157], v[218:221], v[88:91]
	v_mfma_f32_16x16x32_bf16 v[76:79], v[146:149], v[226:229], v[76:79]
	v_mfma_f32_16x16x32_bf16 v[72:75], v[154:157], v[226:229], v[72:75]
	v_mfma_f32_16x16x32_bf16 v[126:129], v[150:153], v[186:189], v[126:129]
	v_mfma_f32_16x16x32_bf16 v[122:125], v[170:173], v[186:189], v[122:125]
	v_mfma_f32_16x16x32_bf16 v[110:113], v[150:153], v[214:217], v[110:113]
	v_mfma_f32_16x16x32_bf16 v[106:109], v[170:173], v[214:217], v[106:109]
	v_mfma_f32_16x16x32_bf16 v[92:95], v[150:153], v[222:225], v[92:95]
	v_mfma_f32_16x16x32_bf16 v[88:91], v[170:173], v[222:225], v[88:91]
	v_mfma_f32_16x16x32_bf16 v[76:79], v[150:153], v[230:233], v[76:79]
	v_mfma_f32_16x16x32_bf16 v[72:75], v[170:173], v[230:233], v[72:75]
	s_barrier
	s_setprio 0
	s_add_i32 s6, s7, s74
	v_lshl_add_u64 v[174:175], s[24:25], 0, v[160:161]
	s_mov_b32 m0, s6
	ds_read_b128 v[182:185], v177 offset:16384
	ds_read_b128 v[186:189], v177 offset:17408
	ds_read_b128 v[190:193], v177 offset:18432
	ds_read_b128 v[214:217], v177 offset:19456
	ds_read_b128 v[218:221], v177 offset:20480
	ds_read_b128 v[222:225], v177 offset:21504
	ds_read_b128 v[226:229], v177 offset:22528
	ds_read_b128 v[230:233], v177 offset:23552
	global_load_lds_dwordx4 v[174:175], off
	s_add_i32 m0, s6, 0x2000
	s_add_u32 s6, s24, 0x20000
	v_lshl_add_u64 v[178:179], s[24:25], 0, v[164:165]
	s_addc_u32 s7, s25, 0
	s_add_i32 s3, s3, s74
	global_load_lds_dwordx4 v[178:179], off
	v_lshl_add_u64 v[180:181], s[6:7], 0, v[160:161]
	s_mov_b32 m0, s3
	v_lshl_add_u64 v[194:195], s[34:35], 0, v[162:163]
	global_load_lds_dwordx4 v[180:181], off
	v_lshl_add_u64 v[180:181], s[6:7], 0, v[164:165]
	s_add_i32 m0, s3, 0x2000
	s_nop 0
	global_load_lds_dwordx4 v[180:181], off
	v_lshl_add_u64 v[180:181], s[34:35], 0, v[158:159]
	s_mov_b32 m0, s75
	s_nop 0
	global_load_lds_dwordx4 v[180:181], off
	s_mov_b32 m0, s82
	s_nop 0
	global_load_lds_dwordx4 v[194:195], off
	s_setprio 1
	s_waitcnt vmcnt(8)
	s_waitcnt lgkmcnt(0)
	s_barrier
	v_mfma_f32_16x16x32_bf16 v[68:71], v[56:59], v[182:185], v[68:71]
	v_mfma_f32_16x16x32_bf16 v[64:67], v[138:141], v[182:185], v[64:67]
	v_mfma_f32_16x16x32_bf16 v[44:47], v[56:59], v[190:193], v[44:47]
	v_mfma_f32_16x16x32_bf16 v[40:43], v[138:141], v[190:193], v[40:43]
	v_mfma_f32_16x16x32_bf16 v[28:31], v[56:59], v[218:221], v[28:31]
	v_mfma_f32_16x16x32_bf16 v[24:27], v[138:141], v[218:221], v[24:27]
	v_mfma_f32_16x16x32_bf16 v[12:15], v[56:59], v[226:229], v[12:15]
	v_mfma_f32_16x16x32_bf16 v[8:11], v[138:141], v[226:229], v[8:11]
	v_mfma_f32_16x16x32_bf16 v[68:71], v[60:63], v[186:189], v[68:71]
	v_mfma_f32_16x16x32_bf16 v[64:67], v[142:145], v[186:189], v[64:67]
	v_mfma_f32_16x16x32_bf16 v[44:47], v[60:63], v[214:217], v[44:47]
	v_mfma_f32_16x16x32_bf16 v[40:43], v[142:145], v[214:217], v[40:43]
	v_mfma_f32_16x16x32_bf16 v[28:31], v[60:63], v[222:225], v[28:31]
	v_mfma_f32_16x16x32_bf16 v[24:27], v[142:145], v[222:225], v[24:27]
	v_mfma_f32_16x16x32_bf16 v[12:15], v[60:63], v[230:233], v[12:15]
	v_mfma_f32_16x16x32_bf16 v[8:11], v[142:145], v[230:233], v[8:11]
	v_mfma_f32_16x16x32_bf16 v[52:55], v[146:149], v[182:185], v[52:55]
	v_mfma_f32_16x16x32_bf16 v[48:51], v[154:157], v[182:185], v[48:51]
	v_mfma_f32_16x16x32_bf16 v[36:39], v[146:149], v[190:193], v[36:39]
	v_mfma_f32_16x16x32_bf16 v[32:35], v[154:157], v[190:193], v[32:35]
	v_mfma_f32_16x16x32_bf16 v[20:23], v[146:149], v[218:221], v[20:23]
	v_mfma_f32_16x16x32_bf16 v[16:19], v[154:157], v[218:221], v[16:19]
	v_mfma_f32_16x16x32_bf16 v[4:7], v[146:149], v[226:229], v[4:7]
	v_mfma_f32_16x16x32_bf16 v[0:3], v[154:157], v[226:229], v[0:3]
	v_mfma_f32_16x16x32_bf16 v[52:55], v[150:153], v[186:189], v[52:55]
	v_mfma_f32_16x16x32_bf16 v[48:51], v[170:173], v[186:189], v[48:51]
	v_mfma_f32_16x16x32_bf16 v[36:39], v[150:153], v[214:217], v[36:39]
	v_mfma_f32_16x16x32_bf16 v[32:35], v[170:173], v[214:217], v[32:35]
	v_mfma_f32_16x16x32_bf16 v[20:23], v[150:153], v[222:225], v[20:23]
	v_mfma_f32_16x16x32_bf16 v[16:19], v[170:173], v[222:225], v[16:19]
	v_mfma_f32_16x16x32_bf16 v[4:7], v[150:153], v[230:233], v[4:7]
	v_mfma_f32_16x16x32_bf16 v[0:3], v[170:173], v[230:233], v[0:3]
	s_barrier
	s_setprio 0
	s_add_i32 s3, 0, 0x18000
	v_add_u32_e32 v96, s3, v176
	s_add_i32 s18, 0, 0x1c000
	ds_read_b128 v[56:59], v96
	ds_read_b128 v[60:63], v96 offset:1024
	ds_read_b128 v[138:141], v96 offset:2048
	ds_read_b128 v[142:145], v96 offset:3072
	v_add_u32_e32 v96, s18, v176
	ds_read_b128 v[146:149], v96
	ds_read_b128 v[150:153], v96 offset:1024
	ds_read_b128 v[154:157], v96 offset:2048
	ds_read_b128 v[170:173], v96 offset:3072
	s_add_u32 s6, s34, 0x20000
	s_addc_u32 s7, s35, 0
	s_mov_b32 m0, s83
	v_lshl_add_u64 v[202:203], s[6:7], 0, v[158:159]
	ds_read_b128 v[182:185], v177 offset:32768
	ds_read_b128 v[186:189], v177 offset:33792
	ds_read_b128 v[190:193], v177 offset:34816
	ds_read_b128 v[214:217], v177 offset:35840
	ds_read_b128 v[218:221], v177 offset:36864
	ds_read_b128 v[222:225], v177 offset:37888
	ds_read_b128 v[226:229], v177 offset:38912
	ds_read_b128 v[230:233], v177 offset:39936
	global_load_lds_dwordx4 v[202:203], off
	v_lshl_add_u64 v[202:203], s[6:7], 0, v[162:163]
	s_mov_b32 m0, s88
	s_nop 0
	global_load_lds_dwordx4 v[202:203], off
	s_setprio 1
	s_waitcnt vmcnt(8)
	s_waitcnt lgkmcnt(0)
	s_barrier
	v_mfma_f32_16x16x32_bf16 v[134:137], v[56:59], v[182:185], v[134:137]
	v_mfma_f32_16x16x32_bf16 v[130:133], v[138:141], v[182:185], v[130:133]
	v_mfma_f32_16x16x32_bf16 v[118:121], v[56:59], v[190:193], v[118:121]
	v_mfma_f32_16x16x32_bf16 v[114:117], v[138:141], v[190:193], v[114:117]
	v_mfma_f32_16x16x32_bf16 v[102:105], v[56:59], v[218:221], v[102:105]
	v_mfma_f32_16x16x32_bf16 v[98:101], v[138:141], v[218:221], v[98:101]
	v_mfma_f32_16x16x32_bf16 v[84:87], v[56:59], v[226:229], v[84:87]
	v_mfma_f32_16x16x32_bf16 v[80:83], v[138:141], v[226:229], v[80:83]
	v_mfma_f32_16x16x32_bf16 v[134:137], v[60:63], v[186:189], v[134:137]
	v_mfma_f32_16x16x32_bf16 v[130:133], v[142:145], v[186:189], v[130:133]
	v_mfma_f32_16x16x32_bf16 v[118:121], v[60:63], v[214:217], v[118:121]
	v_mfma_f32_16x16x32_bf16 v[114:117], v[142:145], v[214:217], v[114:117]
	v_mfma_f32_16x16x32_bf16 v[102:105], v[60:63], v[222:225], v[102:105]
	v_mfma_f32_16x16x32_bf16 v[98:101], v[142:145], v[222:225], v[98:101]
	v_mfma_f32_16x16x32_bf16 v[84:87], v[60:63], v[230:233], v[84:87]
	v_mfma_f32_16x16x32_bf16 v[80:83], v[142:145], v[230:233], v[80:83]
	v_mfma_f32_16x16x32_bf16 v[126:129], v[146:149], v[182:185], v[126:129]
	v_mfma_f32_16x16x32_bf16 v[122:125], v[154:157], v[182:185], v[122:125]
	v_mfma_f32_16x16x32_bf16 v[110:113], v[146:149], v[190:193], v[110:113]
	v_mfma_f32_16x16x32_bf16 v[106:109], v[154:157], v[190:193], v[106:109]
	v_mfma_f32_16x16x32_bf16 v[92:95], v[146:149], v[218:221], v[92:95]
	v_mfma_f32_16x16x32_bf16 v[88:91], v[154:157], v[218:221], v[88:91]
	v_mfma_f32_16x16x32_bf16 v[76:79], v[146:149], v[226:229], v[76:79]
	v_mfma_f32_16x16x32_bf16 v[72:75], v[154:157], v[226:229], v[72:75]
	v_mfma_f32_16x16x32_bf16 v[126:129], v[150:153], v[186:189], v[126:129]
	v_mfma_f32_16x16x32_bf16 v[122:125], v[170:173], v[186:189], v[122:125]
	v_mfma_f32_16x16x32_bf16 v[110:113], v[150:153], v[214:217], v[110:113]
	v_mfma_f32_16x16x32_bf16 v[106:109], v[170:173], v[214:217], v[106:109]
	v_mfma_f32_16x16x32_bf16 v[92:95], v[150:153], v[222:225], v[92:95]
	v_mfma_f32_16x16x32_bf16 v[88:91], v[170:173], v[222:225], v[88:91]
	v_mfma_f32_16x16x32_bf16 v[76:79], v[150:153], v[230:233], v[76:79]
	v_mfma_f32_16x16x32_bf16 v[72:75], v[170:173], v[230:233], v[72:75]
	s_barrier
	s_setprio 0
	s_add_i32 s3, s3, s74
	v_lshl_add_u64 v[174:175], v[174:175], 0, s[30:31]
	s_mov_b32 m0, s3
	ds_read_b128 v[182:185], v177 offset:49152
	ds_read_b128 v[186:189], v177 offset:50176
	ds_read_b128 v[190:193], v177 offset:51200
	ds_read_b128 v[214:217], v177 offset:52224
	ds_read_b128 v[218:221], v177 offset:53248
	ds_read_b128 v[222:225], v177 offset:54272
	ds_read_b128 v[226:229], v177 offset:55296
	ds_read_b128 v[230:233], v177 offset:56320
	global_load_lds_dwordx4 v[174:175], off
	s_add_i32 m0, s3, 0x2000
	s_add_u32 s6, s24, 0x20080
	v_lshl_add_u64 v[174:175], v[178:179], 0, s[30:31]
	s_addc_u32 s7, s25, 0
	s_add_i32 s3, s18, s74
	global_load_lds_dwordx4 v[174:175], off
	v_lshl_add_u64 v[174:175], s[6:7], 0, v[160:161]
	s_mov_b32 m0, s3
	s_nop 0
	global_load_lds_dwordx4 v[174:175], off
	v_lshl_add_u64 v[174:175], s[6:7], 0, v[164:165]
	s_add_i32 m0, s3, 0x2000
	s_nop 0
	global_load_lds_dwordx4 v[174:175], off
	v_lshl_add_u64 v[174:175], v[180:181], 0, s[30:31]
	s_mov_b32 m0, s97
	s_nop 0
	global_load_lds_dwordx4 v[174:175], off
	v_lshl_add_u64 v[174:175], v[194:195], 0, s[30:31]
	s_mov_b32 m0, s50
	s_nop 0
	global_load_lds_dwordx4 v[174:175], off
	s_setprio 1
	s_waitcnt vmcnt(8)
	s_waitcnt lgkmcnt(0)
	s_barrier
	v_mfma_f32_16x16x32_bf16 v[68:71], v[56:59], v[182:185], v[68:71]
	v_mfma_f32_16x16x32_bf16 v[64:67], v[138:141], v[182:185], v[64:67]
	v_mfma_f32_16x16x32_bf16 v[44:47], v[56:59], v[190:193], v[44:47]
	v_mfma_f32_16x16x32_bf16 v[40:43], v[138:141], v[190:193], v[40:43]
	v_mfma_f32_16x16x32_bf16 v[28:31], v[56:59], v[218:221], v[28:31]
	v_mfma_f32_16x16x32_bf16 v[24:27], v[138:141], v[218:221], v[24:27]
	v_mfma_f32_16x16x32_bf16 v[12:15], v[56:59], v[226:229], v[12:15]
	v_mfma_f32_16x16x32_bf16 v[8:11], v[138:141], v[226:229], v[8:11]
	v_mfma_f32_16x16x32_bf16 v[68:71], v[60:63], v[186:189], v[68:71]
	v_mfma_f32_16x16x32_bf16 v[64:67], v[142:145], v[186:189], v[64:67]
	v_mfma_f32_16x16x32_bf16 v[44:47], v[60:63], v[214:217], v[44:47]
	v_mfma_f32_16x16x32_bf16 v[40:43], v[142:145], v[214:217], v[40:43]
	v_mfma_f32_16x16x32_bf16 v[28:31], v[60:63], v[222:225], v[28:31]
	v_mfma_f32_16x16x32_bf16 v[24:27], v[142:145], v[222:225], v[24:27]
	v_mfma_f32_16x16x32_bf16 v[12:15], v[60:63], v[230:233], v[12:15]
	v_mfma_f32_16x16x32_bf16 v[8:11], v[142:145], v[230:233], v[8:11]
	v_mfma_f32_16x16x32_bf16 v[52:55], v[146:149], v[182:185], v[52:55]
	v_mfma_f32_16x16x32_bf16 v[48:51], v[154:157], v[182:185], v[48:51]
	v_mfma_f32_16x16x32_bf16 v[36:39], v[146:149], v[190:193], v[36:39]
	v_mfma_f32_16x16x32_bf16 v[32:35], v[154:157], v[190:193], v[32:35]
	v_mfma_f32_16x16x32_bf16 v[20:23], v[146:149], v[218:221], v[20:23]
	v_mfma_f32_16x16x32_bf16 v[16:19], v[154:157], v[218:221], v[16:19]
	v_mfma_f32_16x16x32_bf16 v[4:7], v[146:149], v[226:229], v[4:7]
	v_mfma_f32_16x16x32_bf16 v[0:3], v[154:157], v[226:229], v[0:3]
	v_mfma_f32_16x16x32_bf16 v[52:55], v[150:153], v[186:189], v[52:55]
	v_mfma_f32_16x16x32_bf16 v[48:51], v[170:173], v[186:189], v[48:51]
	v_mfma_f32_16x16x32_bf16 v[36:39], v[150:153], v[214:217], v[36:39]
	v_mfma_f32_16x16x32_bf16 v[32:35], v[170:173], v[214:217], v[32:35]
	v_mfma_f32_16x16x32_bf16 v[20:23], v[150:153], v[222:225], v[20:23]
	v_mfma_f32_16x16x32_bf16 v[16:19], v[170:173], v[222:225], v[16:19]
	v_mfma_f32_16x16x32_bf16 v[4:7], v[150:153], v[230:233], v[4:7]
	v_mfma_f32_16x16x32_bf16 v[0:3], v[170:173], v[230:233], v[0:3]
	s_barrier
	s_setprio 0
	s_add_i32 s2, s2, 2
	s_add_u32 s22, s22, 0x100
	s_addc_u32 s23, s23, 0
	s_add_u32 s15, s15, 0x100
	s_addc_u32 s17, s17, 0
	s_cmp_gt_u32 s2, 5
	s_cbranch_scc0 .LBB0_421
	s_nop 0
	s_nop 0
	s_nop 0
	s_nop 0
	s_nop 0
	s_nop 0
	s_nop 0
	s_nop 0
	s_nop 0
	s_nop 0
	s_nop 0
	s_nop 0
	s_and_b64 vcc, exec, s[58:59]
	s_cbranch_vccz .LBB0_424
	s_barrier

.LBB0_717:
	s_add_u32 s3, s42, 0xfffe0080
	s_addc_u32 s6, s43, -1
	s_add_i32 s7, 0, 0x10000
	s_cmp_eq_u32 s2, 4
	s_cselect_b32 s47, s23, s6
	s_cselect_b32 s46, s51, s3
	v_add_u32_e32 v140, s7, v143
	s_cselect_b32 s45, s15, s54
	s_cselect_b32 s44, s52, s53
	s_add_i32 s3, 0, 0x14000
	ds_read_b128 v[146:149], v140
	ds_read_b128 v[150:153], v140 offset:1024
	ds_read_b128 v[154:157], v140 offset:2048
	ds_read_b128 v[158:161], v140 offset:3072
	v_add_u32_e32 v140, s3, v143
	ds_read_b128 v[162:165], v140
	ds_read_b128 v[166:169], v140 offset:1024
	ds_read_b128 v[170:173], v140 offset:2048
	ds_read_b128 v[174:177], v140 offset:3072
	v_lshl_add_u64 v[140:141], s[42:43], 0, v[136:137]
	s_add_i32 m0, s20, 0xc000
	ds_read_b128 v[178:181], v145
	ds_read_b128 v[182:185], v145 offset:1024
	ds_read_b128 v[186:189], v145 offset:2048
	ds_read_b128 v[190:193], v145 offset:3072
	ds_read_b128 v[202:205], v145 offset:4096
	ds_read_b128 v[206:209], v145 offset:5120
	ds_read_b128 v[214:217], v145 offset:6144
	ds_read_b128 v[218:221], v145 offset:7168
	global_load_lds_dwordx4 v[140:141], off
	v_lshl_add_u64 v[140:141], s[42:43], 0, v[138:139]
	s_add_i32 m0, s20, 0xe000
	s_nop 0
	global_load_lds_dwordx4 v[140:141], off
	s_setprio 1
	s_waitcnt vmcnt(8)
	s_waitcnt lgkmcnt(0)
	s_barrier
	v_mfma_f32_16x16x32_bf16 v[126:129], v[146:149], v[178:181], v[126:129]
	v_mfma_f32_16x16x32_bf16 v[122:125], v[154:157], v[178:181], v[122:125]
	v_mfma_f32_16x16x32_bf16 v[118:121], v[146:149], v[186:189], v[118:121]
	v_mfma_f32_16x16x32_bf16 v[110:113], v[154:157], v[186:189], v[110:113]
	v_mfma_f32_16x16x32_bf16 v[102:105], v[146:149], v[202:205], v[102:105]
	v_mfma_f32_16x16x32_bf16 v[92:95], v[154:157], v[202:205], v[92:95]
	v_mfma_f32_16x16x32_bf16 v[84:87], v[146:149], v[214:217], v[84:87]
	v_mfma_f32_16x16x32_bf16 v[76:79], v[154:157], v[214:217], v[76:79]
	v_mfma_f32_16x16x32_bf16 v[126:129], v[150:153], v[182:185], v[126:129]
	v_mfma_f32_16x16x32_bf16 v[122:125], v[158:161], v[182:185], v[122:125]
	v_mfma_f32_16x16x32_bf16 v[118:121], v[150:153], v[190:193], v[118:121]
	v_mfma_f32_16x16x32_bf16 v[110:113], v[158:161], v[190:193], v[110:113]
	v_mfma_f32_16x16x32_bf16 v[102:105], v[150:153], v[206:209], v[102:105]
	v_mfma_f32_16x16x32_bf16 v[92:95], v[158:161], v[206:209], v[92:95]
	v_mfma_f32_16x16x32_bf16 v[84:87], v[150:153], v[218:221], v[84:87]
	v_mfma_f32_16x16x32_bf16 v[76:79], v[158:161], v[218:221], v[76:79]
	v_mfma_f32_16x16x32_bf16 v[114:117], v[162:165], v[178:181], v[114:117]
	v_mfma_f32_16x16x32_bf16 v[106:109], v[170:173], v[178:181], v[106:109]
	v_mfma_f32_16x16x32_bf16 v[98:101], v[162:165], v[186:189], v[98:101]
	v_mfma_f32_16x16x32_bf16 v[88:91], v[170:173], v[186:189], v[88:91]
	v_mfma_f32_16x16x32_bf16 v[80:83], v[162:165], v[202:205], v[80:83]
	v_mfma_f32_16x16x32_bf16 v[72:75], v[170:173], v[202:205], v[72:75]
	v_mfma_f32_16x16x32_bf16 v[68:71], v[162:165], v[214:217], v[68:71]
	v_mfma_f32_16x16x32_bf16 v[64:67], v[170:173], v[214:217], v[64:67]
	v_mfma_f32_16x16x32_bf16 v[114:117], v[166:169], v[182:185], v[114:117]
	v_mfma_f32_16x16x32_bf16 v[106:109], v[174:177], v[182:185], v[106:109]
	v_mfma_f32_16x16x32_bf16 v[98:101], v[166:169], v[190:193], v[98:101]
	v_mfma_f32_16x16x32_bf16 v[88:91], v[174:177], v[190:193], v[88:91]
	v_mfma_f32_16x16x32_bf16 v[80:83], v[166:169], v[206:209], v[80:83]
	v_mfma_f32_16x16x32_bf16 v[72:75], v[174:177], v[206:209], v[72:75]
	v_mfma_f32_16x16x32_bf16 v[68:71], v[166:169], v[218:221], v[68:71]
	v_mfma_f32_16x16x32_bf16 v[64:67], v[174:177], v[218:221], v[64:67]
	s_barrier
	s_setprio 0
	s_add_i32 s6, s7, s4
	v_lshl_add_u64 v[140:141], s[44:45], 0, v[96:97]
	s_mov_b32 m0, s6
	ds_read_b128 v[178:181], v145 offset:16384
	ds_read_b128 v[182:185], v145 offset:17408
	ds_read_b128 v[186:189], v145 offset:18432
	ds_read_b128 v[190:193], v145 offset:19456
	ds_read_b128 v[202:205], v145 offset:20480
	ds_read_b128 v[206:209], v145 offset:21504
	ds_read_b128 v[214:217], v145 offset:22528
	ds_read_b128 v[218:221], v145 offset:23552
	global_load_lds_dwordx4 v[140:141], off
	s_add_i32 m0, s6, 0x2000
	s_add_u32 s6, s44, 0x20000
	v_lshl_add_u64 v[194:195], s[44:45], 0, v[134:135]
	s_addc_u32 s7, s45, 0
	s_add_i32 s3, s3, s4
	global_load_lds_dwordx4 v[194:195], off
	v_lshl_add_u64 v[198:199], s[6:7], 0, v[96:97]
	s_mov_b32 m0, s3
	v_lshl_add_u64 v[200:201], s[46:47], 0, v[132:133]
	global_load_lds_dwordx4 v[198:199], off
	v_lshl_add_u64 v[198:199], s[6:7], 0, v[134:135]
	s_add_i32 m0, s3, 0x2000
	s_nop 0
	global_load_lds_dwordx4 v[198:199], off
	v_lshl_add_u64 v[198:199], s[46:47], 0, v[130:131]
	s_mov_b32 m0, s20
	s_nop 0
	global_load_lds_dwordx4 v[198:199], off
	s_mov_b32 m0, s25
	s_nop 0
	global_load_lds_dwordx4 v[200:201], off
	s_setprio 1
	s_waitcnt vmcnt(8)
	s_waitcnt lgkmcnt(0)
	s_barrier
	v_mfma_f32_16x16x32_bf16 v[60:63], v[146:149], v[178:181], v[60:63]
	v_mfma_f32_16x16x32_bf16 v[56:59], v[154:157], v[178:181], v[56:59]
	v_mfma_f32_16x16x32_bf16 v[52:55], v[146:149], v[186:189], v[52:55]
	v_mfma_f32_16x16x32_bf16 v[44:47], v[154:157], v[186:189], v[44:47]
	v_mfma_f32_16x16x32_bf16 v[36:39], v[146:149], v[202:205], v[36:39]
	v_mfma_f32_16x16x32_bf16 v[28:31], v[154:157], v[202:205], v[28:31]
	v_mfma_f32_16x16x32_bf16 v[20:23], v[146:149], v[214:217], v[20:23]
	v_mfma_f32_16x16x32_bf16 v[12:15], v[154:157], v[214:217], v[12:15]
	v_mfma_f32_16x16x32_bf16 v[60:63], v[150:153], v[182:185], v[60:63]
	v_mfma_f32_16x16x32_bf16 v[56:59], v[158:161], v[182:185], v[56:59]
	v_mfma_f32_16x16x32_bf16 v[52:55], v[150:153], v[190:193], v[52:55]
	v_mfma_f32_16x16x32_bf16 v[44:47], v[158:161], v[190:193], v[44:47]
	v_mfma_f32_16x16x32_bf16 v[36:39], v[150:153], v[206:209], v[36:39]
	v_mfma_f32_16x16x32_bf16 v[28:31], v[158:161], v[206:209], v[28:31]
	v_mfma_f32_16x16x32_bf16 v[20:23], v[150:153], v[218:221], v[20:23]
	v_mfma_f32_16x16x32_bf16 v[12:15], v[158:161], v[218:221], v[12:15]
	v_mfma_f32_16x16x32_bf16 v[48:51], v[162:165], v[178:181], v[48:51]
	v_mfma_f32_16x16x32_bf16 v[40:43], v[170:173], v[178:181], v[40:43]
	v_mfma_f32_16x16x32_bf16 v[32:35], v[162:165], v[186:189], v[32:35]
	v_mfma_f32_16x16x32_bf16 v[24:27], v[170:173], v[186:189], v[24:27]
	v_mfma_f32_16x16x32_bf16 v[16:19], v[162:165], v[202:205], v[16:19]
	v_mfma_f32_16x16x32_bf16 v[8:11], v[170:173], v[202:205], v[8:11]
	v_mfma_f32_16x16x32_bf16 v[4:7], v[162:165], v[214:217], v[4:7]
	v_mfma_f32_16x16x32_bf16 v[0:3], v[170:173], v[214:217], v[0:3]
	v_mfma_f32_16x16x32_bf16 v[48:51], v[166:169], v[182:185], v[48:51]
	v_mfma_f32_16x16x32_bf16 v[40:43], v[174:177], v[182:185], v[40:43]
	v_mfma_f32_16x16x32_bf16 v[32:35], v[166:169], v[190:193], v[32:35]
	v_mfma_f32_16x16x32_bf16 v[24:27], v[174:177], v[190:193], v[24:27]
	v_mfma_f32_16x16x32_bf16 v[16:19], v[166:169], v[206:209], v[16:19]
	v_mfma_f32_16x16x32_bf16 v[8:11], v[174:177], v[206:209], v[8:11]
	v_mfma_f32_16x16x32_bf16 v[4:7], v[166:169], v[218:221], v[4:7]
	v_mfma_f32_16x16x32_bf16 v[0:3], v[174:177], v[218:221], v[0:3]
	s_barrier
	s_setprio 0
	s_add_i32 s3, 0, 0x18000
	s_add_i32 s55, 0, 0x1c000
	v_add_u32_e32 v158, s3, v143
	v_add_u32_e32 v174, s55, v143
	ds_read_b128 v[146:149], v158
	ds_read_b128 v[150:153], v158 offset:1024
	ds_read_b128 v[154:157], v158 offset:2048
	ds_read_b128 v[158:161], v158 offset:3072
	ds_read_b128 v[162:165], v174
	ds_read_b128 v[166:169], v174 offset:1024
	ds_read_b128 v[170:173], v174 offset:2048
	ds_read_b128 v[174:177], v174 offset:3072
	s_add_u32 s6, s46, 0x20000
	s_addc_u32 s7, s47, 0
	s_mov_b32 m0, s36
	v_lshl_add_u64 v[222:223], s[6:7], 0, v[130:131]
	ds_read_b128 v[178:181], v145 offset:32768
	ds_read_b128 v[182:185], v145 offset:33792
	ds_read_b128 v[186:189], v145 offset:34816
	ds_read_b128 v[190:193], v145 offset:35840
	ds_read_b128 v[202:205], v145 offset:36864
	ds_read_b128 v[206:209], v145 offset:37888
	ds_read_b128 v[214:217], v145 offset:38912
	ds_read_b128 v[218:221], v145 offset:39936
	global_load_lds_dwordx4 v[222:223], off
	v_lshl_add_u64 v[222:223], s[6:7], 0, v[132:133]
	s_mov_b32 m0, s37
	s_nop 0
	global_load_lds_dwordx4 v[222:223], off
	s_setprio 1
	s_waitcnt vmcnt(8)
	s_waitcnt lgkmcnt(0)
	s_barrier
	v_mfma_f32_16x16x32_bf16 v[126:129], v[146:149], v[178:181], v[126:129]
	v_mfma_f32_16x16x32_bf16 v[122:125], v[154:157], v[178:181], v[122:125]
	v_mfma_f32_16x16x32_bf16 v[118:121], v[146:149], v[186:189], v[118:121]
	v_mfma_f32_16x16x32_bf16 v[110:113], v[154:157], v[186:189], v[110:113]
	v_mfma_f32_16x16x32_bf16 v[102:105], v[146:149], v[202:205], v[102:105]
	v_mfma_f32_16x16x32_bf16 v[92:95], v[154:157], v[202:205], v[92:95]
	v_mfma_f32_16x16x32_bf16 v[84:87], v[146:149], v[214:217], v[84:87]
	v_mfma_f32_16x16x32_bf16 v[76:79], v[154:157], v[214:217], v[76:79]
	v_mfma_f32_16x16x32_bf16 v[126:129], v[150:153], v[182:185], v[126:129]
	v_mfma_f32_16x16x32_bf16 v[122:125], v[158:161], v[182:185], v[122:125]
	v_mfma_f32_16x16x32_bf16 v[118:121], v[150:153], v[190:193], v[118:121]
	v_mfma_f32_16x16x32_bf16 v[110:113], v[158:161], v[190:193], v[110:113]
	v_mfma_f32_16x16x32_bf16 v[102:105], v[150:153], v[206:209], v[102:105]
	v_mfma_f32_16x16x32_bf16 v[92:95], v[158:161], v[206:209], v[92:95]
	v_mfma_f32_16x16x32_bf16 v[84:87], v[150:153], v[218:221], v[84:87]
	v_mfma_f32_16x16x32_bf16 v[76:79], v[158:161], v[218:221], v[76:79]
	v_mfma_f32_16x16x32_bf16 v[114:117], v[162:165], v[178:181], v[114:117]
	v_mfma_f32_16x16x32_bf16 v[106:109], v[170:173], v[178:181], v[106:109]
	v_mfma_f32_16x16x32_bf16 v[98:101], v[162:165], v[186:189], v[98:101]
	v_mfma_f32_16x16x32_bf16 v[88:91], v[170:173], v[186:189], v[88:91]
	v_mfma_f32_16x16x32_bf16 v[80:83], v[162:165], v[202:205], v[80:83]
	v_mfma_f32_16x16x32_bf16 v[72:75], v[170:173], v[202:205], v[72:75]
	v_mfma_f32_16x16x32_bf16 v[68:71], v[162:165], v[214:217], v[68:71]
	v_mfma_f32_16x16x32_bf16 v[64:67], v[170:173], v[214:217], v[64:67]
	v_mfma_f32_16x16x32_bf16 v[114:117], v[166:169], v[182:185], v[114:117]
	v_mfma_f32_16x16x32_bf16 v[106:109], v[174:177], v[182:185], v[106:109]
	v_mfma_f32_16x16x32_bf16 v[98:101], v[166:169], v[190:193], v[98:101]
	v_mfma_f32_16x16x32_bf16 v[88:91], v[174:177], v[190:193], v[88:91]
	v_mfma_f32_16x16x32_bf16 v[80:83], v[166:169], v[206:209], v[80:83]
	v_mfma_f32_16x16x32_bf16 v[72:75], v[174:177], v[206:209], v[72:75]
	v_mfma_f32_16x16x32_bf16 v[68:71], v[166:169], v[218:221], v[68:71]
	v_mfma_f32_16x16x32_bf16 v[64:67], v[174:177], v[218:221], v[64:67]
	s_barrier
	s_setprio 0
	s_add_i32 s3, s3, s4
	v_lshl_add_u64 v[140:141], v[140:141], 0, s[30:31]
	s_mov_b32 m0, s3
	ds_read_b128 v[178:181], v145 offset:49152
	ds_read_b128 v[182:185], v145 offset:50176
	ds_read_b128 v[186:189], v145 offset:51200
	ds_read_b128 v[190:193], v145 offset:52224
	ds_read_b128 v[202:205], v145 offset:53248
	ds_read_b128 v[206:209], v145 offset:54272
	ds_read_b128 v[214:217], v145 offset:55296
	ds_read_b128 v[218:221], v145 offset:56320
	global_load_lds_dwordx4 v[140:141], off
	s_add_i32 m0, s3, 0x2000
	s_add_u32 s6, s44, 0x20080
	v_lshl_add_u64 v[140:141], v[194:195], 0, s[30:31]
	s_addc_u32 s7, s45, 0
	s_add_i32 s3, s55, s4
	global_load_lds_dwordx4 v[140:141], off
	v_lshl_add_u64 v[140:141], s[6:7], 0, v[96:97]
	s_mov_b32 m0, s3
	s_nop 0
	global_load_lds_dwordx4 v[140:141], off
	v_lshl_add_u64 v[140:141], s[6:7], 0, v[134:135]
	s_add_i32 m0, s3, 0x2000
	s_nop 0
	global_load_lds_dwordx4 v[140:141], off
	v_lshl_add_u64 v[140:141], v[198:199], 0, s[30:31]
	s_mov_b32 m0, s40
	s_nop 0
	global_load_lds_dwordx4 v[140:141], off
	v_lshl_add_u64 v[140:141], v[200:201], 0, s[30:31]
	s_mov_b32 m0, s48
	s_nop 0
	global_load_lds_dwordx4 v[140:141], off
	s_setprio 1
	s_waitcnt vmcnt(8)
	s_waitcnt lgkmcnt(0)
	s_barrier
	v_mfma_f32_16x16x32_bf16 v[60:63], v[146:149], v[178:181], v[60:63]
	v_mfma_f32_16x16x32_bf16 v[56:59], v[154:157], v[178:181], v[56:59]
	v_mfma_f32_16x16x32_bf16 v[52:55], v[146:149], v[186:189], v[52:55]
	v_mfma_f32_16x16x32_bf16 v[44:47], v[154:157], v[186:189], v[44:47]
	v_mfma_f32_16x16x32_bf16 v[36:39], v[146:149], v[202:205], v[36:39]
	v_mfma_f32_16x16x32_bf16 v[28:31], v[154:157], v[202:205], v[28:31]
	v_mfma_f32_16x16x32_bf16 v[20:23], v[146:149], v[214:217], v[20:23]
	v_mfma_f32_16x16x32_bf16 v[12:15], v[154:157], v[214:217], v[12:15]
	v_mfma_f32_16x16x32_bf16 v[60:63], v[150:153], v[182:185], v[60:63]
	v_mfma_f32_16x16x32_bf16 v[56:59], v[158:161], v[182:185], v[56:59]
	v_mfma_f32_16x16x32_bf16 v[52:55], v[150:153], v[190:193], v[52:55]
	v_mfma_f32_16x16x32_bf16 v[44:47], v[158:161], v[190:193], v[44:47]
	v_mfma_f32_16x16x32_bf16 v[36:39], v[150:153], v[206:209], v[36:39]
	v_mfma_f32_16x16x32_bf16 v[28:31], v[158:161], v[206:209], v[28:31]
	v_mfma_f32_16x16x32_bf16 v[20:23], v[150:153], v[218:221], v[20:23]
	v_mfma_f32_16x16x32_bf16 v[12:15], v[158:161], v[218:221], v[12:15]
	v_mfma_f32_16x16x32_bf16 v[48:51], v[162:165], v[178:181], v[48:51]
	v_mfma_f32_16x16x32_bf16 v[40:43], v[170:173], v[178:181], v[40:43]
	v_mfma_f32_16x16x32_bf16 v[32:35], v[162:165], v[186:189], v[32:35]
	v_mfma_f32_16x16x32_bf16 v[24:27], v[170:173], v[186:189], v[24:27]
	v_mfma_f32_16x16x32_bf16 v[16:19], v[162:165], v[202:205], v[16:19]
	v_mfma_f32_16x16x32_bf16 v[8:11], v[170:173], v[202:205], v[8:11]
	v_mfma_f32_16x16x32_bf16 v[4:7], v[162:165], v[214:217], v[4:7]
	v_mfma_f32_16x16x32_bf16 v[0:3], v[170:173], v[214:217], v[0:3]
	v_mfma_f32_16x16x32_bf16 v[48:51], v[166:169], v[182:185], v[48:51]
	v_mfma_f32_16x16x32_bf16 v[40:43], v[174:177], v[182:185], v[40:43]
	v_mfma_f32_16x16x32_bf16 v[32:35], v[166:169], v[190:193], v[32:35]
	v_mfma_f32_16x16x32_bf16 v[24:27], v[174:177], v[190:193], v[24:27]
	v_mfma_f32_16x16x32_bf16 v[16:19], v[166:169], v[206:209], v[16:19]
	v_mfma_f32_16x16x32_bf16 v[8:11], v[174:177], v[206:209], v[8:11]
	v_mfma_f32_16x16x32_bf16 v[4:7], v[166:169], v[218:221], v[4:7]
	v_mfma_f32_16x16x32_bf16 v[0:3], v[174:177], v[218:221], v[0:3]
	s_barrier
	s_setprio 0
	s_add_i32 s2, s2, 2
	s_add_u32 s42, s42, 0x100
	s_addc_u32 s43, s43, 0
	s_add_u32 s53, s53, 0x100
	s_addc_u32 s54, s54, 0
	s_cmp_gt_u32 s2, 5
	s_cbranch_scc0 .LBB0_717
	s_nop 0
	s_nop 0
	s_nop 0
	s_nop 0
	s_nop 0
	s_nop 0
	s_nop 0
	s_nop 0
	s_nop 0
	s_nop 0
	s_nop 0
	s_nop 0
	v_readlane_b32 s54, v254, 56
	s_and_b64 vcc, exec, s[10:11]
	v_readlane_b32 s55, v254, 57
	s_cbranch_vccz .LBB0_720
	s_barrier

.LBB0_993:
	s_add_u32 s3, s24, s46
	s_addc_u32 s6, s25, s47
	s_add_u32 s3, s3, 0x100
	s_addc_u32 s6, s6, 0
	s_add_u32 s48, s59, s46
	s_addc_u32 s49, s60, s47
	s_add_i32 s63, 0, 0x10000
	s_cmpk_eq_i32 s46, 0xf00
	s_cselect_b32 s51, s23, s6
	s_cselect_b32 s50, s61, s3
	v_add_u32_e32 v146, s63, v144
	s_cselect_b32 s49, s15, s49
	s_cselect_b32 s48, s62, s48
	s_add_i32 s3, 0, 0x14000
	ds_read_b128 v[154:157], v146
	ds_read_b128 v[158:161], v146 offset:1024
	ds_read_b128 v[162:165], v146 offset:2048
	ds_read_b128 v[166:169], v146 offset:3072
	v_add_u32_e32 v146, s3, v144
	ds_read_b128 v[174:177], v146
	ds_read_b128 v[178:181], v146 offset:1024
	ds_read_b128 v[182:185], v146 offset:2048
	ds_read_b128 v[186:189], v146 offset:3072
	v_lshl_add_u64 v[146:147], v[140:141], 0, s[46:47]
	s_add_i32 m0, s17, 0xc000
	ds_read_b128 v[190:193], v145
	ds_read_b128 v[202:205], v145 offset:1024
	ds_read_b128 v[206:209], v145 offset:2048
	ds_read_b128 v[214:217], v145 offset:3072
	ds_read_b128 v[218:221], v145 offset:4096
	ds_read_b128 v[222:225], v145 offset:5120
	ds_read_b128 v[226:229], v145 offset:6144
	ds_read_b128 v[230:233], v145 offset:7168
	global_load_lds_dwordx4 v[146:147], off
	v_lshl_add_u64 v[146:147], v[142:143], 0, s[46:47]
	s_add_i32 m0, s17, 0xe000
	s_nop 0
	global_load_lds_dwordx4 v[146:147], off
	s_setprio 1
	s_waitcnt vmcnt(8)
	s_waitcnt lgkmcnt(0)
	s_barrier
	v_mfma_f32_16x16x32_bf16 v[110:113], v[154:157], v[190:193], v[110:113]
	v_mfma_f32_16x16x32_bf16 v[106:109], v[162:165], v[190:193], v[106:109]
	v_mfma_f32_16x16x32_bf16 v[118:121], v[154:157], v[206:209], v[118:121]
	v_mfma_f32_16x16x32_bf16 v[114:117], v[162:165], v[206:209], v[114:117]
	v_mfma_f32_16x16x32_bf16 v[126:129], v[154:157], v[218:221], v[126:129]
	v_mfma_f32_16x16x32_bf16 v[122:125], v[162:165], v[218:221], v[122:125]
	v_mfma_f32_16x16x32_bf16 v[92:95], v[154:157], v[226:229], v[92:95]
	v_mfma_f32_16x16x32_bf16 v[88:91], v[162:165], v[226:229], v[88:91]
	v_mfma_f32_16x16x32_bf16 v[110:113], v[158:161], v[202:205], v[110:113]
	v_mfma_f32_16x16x32_bf16 v[106:109], v[166:169], v[202:205], v[106:109]
	v_mfma_f32_16x16x32_bf16 v[118:121], v[158:161], v[214:217], v[118:121]
	v_mfma_f32_16x16x32_bf16 v[114:117], v[166:169], v[214:217], v[114:117]
	v_mfma_f32_16x16x32_bf16 v[126:129], v[158:161], v[222:225], v[126:129]
	v_mfma_f32_16x16x32_bf16 v[122:125], v[166:169], v[222:225], v[122:125]
	v_mfma_f32_16x16x32_bf16 v[92:95], v[158:161], v[230:233], v[92:95]
	v_mfma_f32_16x16x32_bf16 v[88:91], v[166:169], v[230:233], v[88:91]
	v_mfma_f32_16x16x32_bf16 v[4:7], v[174:177], v[190:193], v[4:7]
	v_mfma_f32_16x16x32_bf16 v[0:3], v[182:185], v[190:193], v[0:3]
	v_mfma_f32_16x16x32_bf16 v[12:15], v[174:177], v[206:209], v[12:15]
	v_mfma_f32_16x16x32_bf16 v[8:11], v[182:185], v[206:209], v[8:11]
	v_mfma_f32_16x16x32_bf16 v[24:27], v[174:177], v[218:221], v[24:27]
	v_mfma_f32_16x16x32_bf16 v[20:23], v[182:185], v[218:221], v[20:23]
	v_mfma_f32_16x16x32_bf16 v[40:43], v[174:177], v[226:229], v[40:43]
	v_mfma_f32_16x16x32_bf16 v[32:35], v[182:185], v[226:229], v[32:35]
	v_mfma_f32_16x16x32_bf16 v[4:7], v[178:181], v[202:205], v[4:7]
	v_mfma_f32_16x16x32_bf16 v[0:3], v[186:189], v[202:205], v[0:3]
	v_mfma_f32_16x16x32_bf16 v[12:15], v[178:181], v[214:217], v[12:15]
	v_mfma_f32_16x16x32_bf16 v[8:11], v[186:189], v[214:217], v[8:11]
	v_mfma_f32_16x16x32_bf16 v[24:27], v[178:181], v[222:225], v[24:27]
	v_mfma_f32_16x16x32_bf16 v[20:23], v[186:189], v[222:225], v[20:23]
	v_mfma_f32_16x16x32_bf16 v[40:43], v[178:181], v[230:233], v[40:43]
	v_mfma_f32_16x16x32_bf16 v[32:35], v[186:189], v[230:233], v[32:35]
	s_barrier
	s_setprio 0
	s_add_i32 s6, s63, s5
	v_lshl_add_u64 v[146:147], s[48:49], 0, v[96:97]
	s_mov_b32 m0, s6
	ds_read_b128 v[190:193], v145 offset:16384
	ds_read_b128 v[202:205], v145 offset:17408
	ds_read_b128 v[206:209], v145 offset:18432
	ds_read_b128 v[214:217], v145 offset:19456
	ds_read_b128 v[218:221], v145 offset:20480
	ds_read_b128 v[222:225], v145 offset:21504
	ds_read_b128 v[226:229], v145 offset:22528
	ds_read_b128 v[230:233], v145 offset:23552
	global_load_lds_dwordx4 v[146:147], off
	s_add_i32 m0, s6, 0x2000
	s_add_u32 s72, s48, 0x80000
	v_lshl_add_u64 v[150:151], s[48:49], 0, v[130:131]
	s_addc_u32 s73, s49, 0
	s_add_i32 s3, s3, s5
	global_load_lds_dwordx4 v[150:151], off
	v_lshl_add_u64 v[170:171], s[72:73], 0, v[96:97]
	s_mov_b32 m0, s3
	v_lshl_add_u64 v[194:195], s[50:51], 0, v[132:133]
	global_load_lds_dwordx4 v[170:171], off
	v_lshl_add_u64 v[170:171], s[72:73], 0, v[130:131]
	s_add_i32 m0, s3, 0x2000
	s_nop 0
	global_load_lds_dwordx4 v[170:171], off
	v_lshl_add_u64 v[170:171], s[50:51], 0, v[134:135]
	s_mov_b32 m0, s17
	s_nop 0
	global_load_lds_dwordx4 v[170:171], off
	s_mov_b32 m0, s18
	s_nop 0
	global_load_lds_dwordx4 v[194:195], off
	s_setprio 1
	s_waitcnt vmcnt(8)
	s_waitcnt lgkmcnt(0)
	s_barrier
	v_mfma_f32_16x16x32_bf16 v[102:105], v[154:157], v[190:193], v[102:105]
	v_mfma_f32_16x16x32_bf16 v[98:101], v[162:165], v[190:193], v[98:101]
	v_mfma_f32_16x16x32_bf16 v[84:87], v[154:157], v[206:209], v[84:87]
	v_mfma_f32_16x16x32_bf16 v[80:83], v[162:165], v[206:209], v[80:83]
	v_mfma_f32_16x16x32_bf16 v[68:71], v[154:157], v[218:221], v[68:71]
	v_mfma_f32_16x16x32_bf16 v[64:67], v[162:165], v[218:221], v[64:67]
	v_mfma_f32_16x16x32_bf16 v[44:47], v[154:157], v[226:229], v[44:47]
	v_mfma_f32_16x16x32_bf16 v[36:39], v[162:165], v[226:229], v[36:39]
	v_mfma_f32_16x16x32_bf16 v[102:105], v[158:161], v[202:205], v[102:105]
	v_mfma_f32_16x16x32_bf16 v[98:101], v[166:169], v[202:205], v[98:101]
	v_mfma_f32_16x16x32_bf16 v[84:87], v[158:161], v[214:217], v[84:87]
	v_mfma_f32_16x16x32_bf16 v[80:83], v[166:169], v[214:217], v[80:83]
	v_mfma_f32_16x16x32_bf16 v[68:71], v[158:161], v[222:225], v[68:71]
	v_mfma_f32_16x16x32_bf16 v[64:67], v[166:169], v[222:225], v[64:67]
	v_mfma_f32_16x16x32_bf16 v[44:47], v[158:161], v[230:233], v[44:47]
	v_mfma_f32_16x16x32_bf16 v[36:39], v[166:169], v[230:233], v[36:39]
	v_mfma_f32_16x16x32_bf16 v[60:63], v[174:177], v[190:193], v[60:63]
	v_mfma_f32_16x16x32_bf16 v[56:59], v[182:185], v[190:193], v[56:59]
	v_mfma_f32_16x16x32_bf16 v[76:79], v[174:177], v[206:209], v[76:79]
	v_mfma_f32_16x16x32_bf16 v[72:75], v[182:185], v[206:209], v[72:75]
	v_mfma_f32_16x16x32_bf16 v[52:55], v[174:177], v[218:221], v[52:55]
	v_mfma_f32_16x16x32_bf16 v[48:51], v[182:185], v[218:221], v[48:51]
	v_mfma_f32_16x16x32_bf16 v[28:31], v[174:177], v[226:229], v[28:31]
	v_mfma_f32_16x16x32_bf16 v[16:19], v[182:185], v[226:229], v[16:19]
	v_mfma_f32_16x16x32_bf16 v[60:63], v[178:181], v[202:205], v[60:63]
	v_mfma_f32_16x16x32_bf16 v[56:59], v[186:189], v[202:205], v[56:59]
	v_mfma_f32_16x16x32_bf16 v[76:79], v[178:181], v[214:217], v[76:79]
	v_mfma_f32_16x16x32_bf16 v[72:75], v[186:189], v[214:217], v[72:75]
	v_mfma_f32_16x16x32_bf16 v[52:55], v[178:181], v[222:225], v[52:55]
	v_mfma_f32_16x16x32_bf16 v[48:51], v[186:189], v[222:225], v[48:51]
	v_mfma_f32_16x16x32_bf16 v[28:31], v[178:181], v[230:233], v[28:31]
	v_mfma_f32_16x16x32_bf16 v[16:19], v[186:189], v[230:233], v[16:19]
	s_barrier
	s_setprio 0
	s_add_i32 s3, 0, 0x18000
	v_add_u32_e32 v149, s3, v144
	s_add_i32 s6, 0, 0x1c000
	ds_read_b128 v[154:157], v149
	ds_read_b128 v[158:161], v149 offset:1024
	ds_read_b128 v[162:165], v149 offset:2048
	ds_read_b128 v[166:169], v149 offset:3072
	v_add_u32_e32 v149, s6, v144
	ds_read_b128 v[174:177], v149
	ds_read_b128 v[178:181], v149 offset:1024
	ds_read_b128 v[182:185], v149 offset:2048
	ds_read_b128 v[186:189], v149 offset:3072
	s_add_u32 s50, s50, 0x80000
	s_addc_u32 s51, s51, 0
	s_mov_b32 m0, s19
	v_lshl_add_u64 v[198:199], s[50:51], 0, v[134:135]
	ds_read_b128 v[190:193], v145 offset:32768
	ds_read_b128 v[202:205], v145 offset:33792
	ds_read_b128 v[206:209], v145 offset:34816
	ds_read_b128 v[214:217], v145 offset:35840
	ds_read_b128 v[218:221], v145 offset:36864
	ds_read_b128 v[222:225], v145 offset:37888
	ds_read_b128 v[226:229], v145 offset:38912
	ds_read_b128 v[230:233], v145 offset:39936
	global_load_lds_dwordx4 v[198:199], off
	v_lshl_add_u64 v[198:199], s[50:51], 0, v[132:133]
	s_mov_b32 m0, s20
	s_nop 0
	global_load_lds_dwordx4 v[198:199], off
	s_setprio 1
	s_waitcnt vmcnt(8)
	s_waitcnt lgkmcnt(0)
	s_barrier
	v_mfma_f32_16x16x32_bf16 v[110:113], v[154:157], v[190:193], v[110:113]
	v_mfma_f32_16x16x32_bf16 v[106:109], v[162:165], v[190:193], v[106:109]
	v_mfma_f32_16x16x32_bf16 v[118:121], v[154:157], v[206:209], v[118:121]
	v_mfma_f32_16x16x32_bf16 v[114:117], v[162:165], v[206:209], v[114:117]
	v_mfma_f32_16x16x32_bf16 v[126:129], v[154:157], v[218:221], v[126:129]
	v_mfma_f32_16x16x32_bf16 v[122:125], v[162:165], v[218:221], v[122:125]
	v_mfma_f32_16x16x32_bf16 v[92:95], v[154:157], v[226:229], v[92:95]
	v_mfma_f32_16x16x32_bf16 v[88:91], v[162:165], v[226:229], v[88:91]
	v_mfma_f32_16x16x32_bf16 v[110:113], v[158:161], v[202:205], v[110:113]
	v_mfma_f32_16x16x32_bf16 v[106:109], v[166:169], v[202:205], v[106:109]
	v_mfma_f32_16x16x32_bf16 v[118:121], v[158:161], v[214:217], v[118:121]
	v_mfma_f32_16x16x32_bf16 v[114:117], v[166:169], v[214:217], v[114:117]
	v_mfma_f32_16x16x32_bf16 v[126:129], v[158:161], v[222:225], v[126:129]
	v_mfma_f32_16x16x32_bf16 v[122:125], v[166:169], v[222:225], v[122:125]
	v_mfma_f32_16x16x32_bf16 v[92:95], v[158:161], v[230:233], v[92:95]
	v_mfma_f32_16x16x32_bf16 v[88:91], v[166:169], v[230:233], v[88:91]
	v_mfma_f32_16x16x32_bf16 v[4:7], v[174:177], v[190:193], v[4:7]
	v_mfma_f32_16x16x32_bf16 v[0:3], v[182:185], v[190:193], v[0:3]
	v_mfma_f32_16x16x32_bf16 v[12:15], v[174:177], v[206:209], v[12:15]
	v_mfma_f32_16x16x32_bf16 v[8:11], v[182:185], v[206:209], v[8:11]
	v_mfma_f32_16x16x32_bf16 v[24:27], v[174:177], v[218:221], v[24:27]
	v_mfma_f32_16x16x32_bf16 v[20:23], v[182:185], v[218:221], v[20:23]
	v_mfma_f32_16x16x32_bf16 v[40:43], v[174:177], v[226:229], v[40:43]
	v_mfma_f32_16x16x32_bf16 v[32:35], v[182:185], v[226:229], v[32:35]
	v_mfma_f32_16x16x32_bf16 v[4:7], v[178:181], v[202:205], v[4:7]
	v_mfma_f32_16x16x32_bf16 v[0:3], v[186:189], v[202:205], v[0:3]
	v_mfma_f32_16x16x32_bf16 v[12:15], v[178:181], v[214:217], v[12:15]
	v_mfma_f32_16x16x32_bf16 v[8:11], v[186:189], v[214:217], v[8:11]
	v_mfma_f32_16x16x32_bf16 v[24:27], v[178:181], v[222:225], v[24:27]
	v_mfma_f32_16x16x32_bf16 v[20:23], v[186:189], v[222:225], v[20:23]
	v_mfma_f32_16x16x32_bf16 v[40:43], v[178:181], v[230:233], v[40:43]
	v_mfma_f32_16x16x32_bf16 v[32:35], v[186:189], v[230:233], v[32:35]
	s_barrier
	s_setprio 0
	s_add_i32 s3, s3, s5
	v_lshl_add_u64 v[146:147], v[146:147], 0, s[30:31]
	s_mov_b32 m0, s3
	ds_read_b128 v[190:193], v145 offset:49152
	ds_read_b128 v[202:205], v145 offset:50176
	ds_read_b128 v[206:209], v145 offset:51200
	ds_read_b128 v[214:217], v145 offset:52224
	ds_read_b128 v[218:221], v145 offset:53248
	ds_read_b128 v[222:225], v145 offset:54272
	ds_read_b128 v[226:229], v145 offset:55296
	ds_read_b128 v[230:233], v145 offset:56320
	global_load_lds_dwordx4 v[146:147], off
	s_add_i32 m0, s3, 0x2000
	s_add_u32 s48, s48, 0x80080
	v_lshl_add_u64 v[146:147], v[150:151], 0, s[30:31]
	s_addc_u32 s49, s49, 0
	s_add_i32 s3, s6, s5
	global_load_lds_dwordx4 v[146:147], off
	v_lshl_add_u64 v[146:147], s[48:49], 0, v[96:97]
	s_mov_b32 m0, s3
	s_nop 0
	global_load_lds_dwordx4 v[146:147], off
	v_lshl_add_u64 v[146:147], s[48:49], 0, v[130:131]
	s_add_i32 m0, s3, 0x2000
	s_nop 0
	global_load_lds_dwordx4 v[146:147], off
	v_lshl_add_u64 v[146:147], v[170:171], 0, s[30:31]
	s_mov_b32 m0, s37
	s_nop 0
	global_load_lds_dwordx4 v[146:147], off
	v_lshl_add_u64 v[146:147], v[194:195], 0, s[30:31]
	s_mov_b32 m0, s56
	s_nop 0
	global_load_lds_dwordx4 v[146:147], off
	s_setprio 1
	s_waitcnt vmcnt(8)
	s_waitcnt lgkmcnt(0)
	s_barrier
	v_mfma_f32_16x16x32_bf16 v[102:105], v[154:157], v[190:193], v[102:105]
	v_mfma_f32_16x16x32_bf16 v[98:101], v[162:165], v[190:193], v[98:101]
	v_mfma_f32_16x16x32_bf16 v[84:87], v[154:157], v[206:209], v[84:87]
	v_mfma_f32_16x16x32_bf16 v[80:83], v[162:165], v[206:209], v[80:83]
	v_mfma_f32_16x16x32_bf16 v[68:71], v[154:157], v[218:221], v[68:71]
	v_mfma_f32_16x16x32_bf16 v[64:67], v[162:165], v[218:221], v[64:67]
	v_mfma_f32_16x16x32_bf16 v[44:47], v[154:157], v[226:229], v[44:47]
	v_mfma_f32_16x16x32_bf16 v[36:39], v[162:165], v[226:229], v[36:39]
	v_mfma_f32_16x16x32_bf16 v[102:105], v[158:161], v[202:205], v[102:105]
	v_mfma_f32_16x16x32_bf16 v[98:101], v[166:169], v[202:205], v[98:101]
	v_mfma_f32_16x16x32_bf16 v[84:87], v[158:161], v[214:217], v[84:87]
	v_mfma_f32_16x16x32_bf16 v[80:83], v[166:169], v[214:217], v[80:83]
	v_mfma_f32_16x16x32_bf16 v[68:71], v[158:161], v[222:225], v[68:71]
	v_mfma_f32_16x16x32_bf16 v[64:67], v[166:169], v[222:225], v[64:67]
	v_mfma_f32_16x16x32_bf16 v[44:47], v[158:161], v[230:233], v[44:47]
	v_mfma_f32_16x16x32_bf16 v[36:39], v[166:169], v[230:233], v[36:39]
	v_mfma_f32_16x16x32_bf16 v[60:63], v[174:177], v[190:193], v[60:63]
	v_mfma_f32_16x16x32_bf16 v[56:59], v[182:185], v[190:193], v[56:59]
	v_mfma_f32_16x16x32_bf16 v[76:79], v[174:177], v[206:209], v[76:79]
	v_mfma_f32_16x16x32_bf16 v[72:75], v[182:185], v[206:209], v[72:75]
	v_mfma_f32_16x16x32_bf16 v[52:55], v[174:177], v[218:221], v[52:55]
	v_mfma_f32_16x16x32_bf16 v[48:51], v[182:185], v[218:221], v[48:51]
	v_mfma_f32_16x16x32_bf16 v[28:31], v[174:177], v[226:229], v[28:31]
	v_mfma_f32_16x16x32_bf16 v[16:19], v[182:185], v[226:229], v[16:19]
	v_mfma_f32_16x16x32_bf16 v[60:63], v[178:181], v[202:205], v[60:63]
	v_mfma_f32_16x16x32_bf16 v[56:59], v[186:189], v[202:205], v[56:59]
	v_mfma_f32_16x16x32_bf16 v[76:79], v[178:181], v[214:217], v[76:79]
	v_mfma_f32_16x16x32_bf16 v[72:75], v[186:189], v[214:217], v[72:75]
	v_mfma_f32_16x16x32_bf16 v[52:55], v[178:181], v[222:225], v[52:55]
	v_mfma_f32_16x16x32_bf16 v[48:51], v[186:189], v[222:225], v[48:51]
	v_mfma_f32_16x16x32_bf16 v[28:31], v[178:181], v[230:233], v[28:31]
	v_mfma_f32_16x16x32_bf16 v[16:19], v[186:189], v[230:233], v[16:19]
	s_barrier
	s_setprio 0
	s_add_i32 s2, s2, 2
	s_add_u32 s46, s46, 0x100
	s_addc_u32 s47, s47, 0
	s_cmp_gt_u32 s2, 29
	s_cbranch_scc0 .LBB0_993
	s_nop 0
	s_nop 0
	s_nop 0
	s_nop 0
	s_nop 0
	s_nop 0
	s_nop 0
	s_nop 0
	s_nop 0
	s_nop 0
	s_nop 0
	s_nop 0
	s_and_b64 vcc, exec, s[12:13]
	s_cbranch_vccz .LBB0_996
	s_barrier

.LBB0_1158:
	s_add_u32 s34, s62, 0x100
	s_addc_u32 s35, s63, 0
	s_add_i32 s67, 0, 0x10000
	s_cmp_eq_u32 s6, 28
	s_cselect_b32 s89, s23, s35
	s_cselect_b32 s88, s61, s34
	s_cselect_b32 vcc_hi, s91, s3
	s_cselect_b32 vcc_lo, s93, s2
	s_add_i32 s76, 0, 0x14000
	v_add_u32_e32 v142, s67, v191
	v_add_u32_e32 v158, s76, v191
	ds_read_b128 v[130:133], v142
	ds_read_b128 v[134:137], v142 offset:1024
	ds_read_b128 v[138:141], v142 offset:2048
	ds_read_b128 v[142:145], v142 offset:3072
	ds_read_b128 v[146:149], v158
	ds_read_b128 v[150:153], v158 offset:1024
	ds_read_b128 v[154:157], v158 offset:2048
	ds_read_b128 v[158:161], v158 offset:3072
	v_lshl_add_u64 v[188:189], s[62:63], 0, v[184:185]
	s_add_i32 m0, s17, 0xc000
	ds_read_b128 v[162:165], v224
	ds_read_b128 v[166:169], v224 offset:1024
	ds_read_b128 v[170:173], v224 offset:2048
	ds_read_b128 v[178:181], v224 offset:3072
	ds_read_b128 v[202:205], v224 offset:4096
	ds_read_b128 v[206:209], v224 offset:5120
	ds_read_b128 v[226:229], v224 offset:6144
	ds_read_b128 v[230:233], v224 offset:7168
	global_load_lds_dwordx4 v[188:189], off
	v_lshl_add_u64 v[188:189], s[62:63], 0, v[186:187]
	s_add_i32 m0, s17, 0xe000
	s_nop 0
	global_load_lds_dwordx4 v[188:189], off
	s_setprio 1
	s_waitcnt vmcnt(8)
	s_waitcnt lgkmcnt(0)
	s_barrier
	v_mfma_f32_16x16x32_bf16 v[126:129], v[130:133], v[162:165], v[126:129]
	v_mfma_f32_16x16x32_bf16 v[56:59], v[138:141], v[162:165], v[56:59]
	v_mfma_f32_16x16x32_bf16 v[122:125], v[130:133], v[170:173], v[122:125]
	v_mfma_f32_16x16x32_bf16 v[52:55], v[138:141], v[170:173], v[52:55]
	v_mfma_f32_16x16x32_bf16 v[118:121], v[130:133], v[202:205], v[118:121]
	v_mfma_f32_16x16x32_bf16 v[60:63], v[138:141], v[202:205], v[60:63]
	v_mfma_f32_16x16x32_bf16 v[114:117], v[130:133], v[226:229], v[114:117]
	v_mfma_f32_16x16x32_bf16 v[44:47], v[138:141], v[226:229], v[44:47]
	v_mfma_f32_16x16x32_bf16 v[126:129], v[134:137], v[166:169], v[126:129]
	v_mfma_f32_16x16x32_bf16 v[56:59], v[142:145], v[166:169], v[56:59]
	v_mfma_f32_16x16x32_bf16 v[122:125], v[134:137], v[178:181], v[122:125]
	v_mfma_f32_16x16x32_bf16 v[52:55], v[142:145], v[178:181], v[52:55]
	v_mfma_f32_16x16x32_bf16 v[118:121], v[134:137], v[206:209], v[118:121]
	v_mfma_f32_16x16x32_bf16 v[60:63], v[142:145], v[206:209], v[60:63]
	v_mfma_f32_16x16x32_bf16 v[114:117], v[134:137], v[230:233], v[114:117]
	v_mfma_f32_16x16x32_bf16 v[44:47], v[142:145], v[230:233], v[44:47]
	v_mfma_f32_16x16x32_bf16 v[110:113], v[146:149], v[162:165], v[110:113]
	v_mfma_f32_16x16x32_bf16 v[40:43], v[154:157], v[162:165], v[40:43]
	v_mfma_f32_16x16x32_bf16 v[106:109], v[146:149], v[170:173], v[106:109]
	v_mfma_f32_16x16x32_bf16 v[36:39], v[154:157], v[170:173], v[36:39]
	v_mfma_f32_16x16x32_bf16 v[102:105], v[146:149], v[202:205], v[102:105]
	v_mfma_f32_16x16x32_bf16 v[48:51], v[154:157], v[202:205], v[48:51]
	v_mfma_f32_16x16x32_bf16 v[98:101], v[146:149], v[226:229], v[98:101]
	v_mfma_f32_16x16x32_bf16 v[32:35], v[154:157], v[226:229], v[32:35]
	v_mfma_f32_16x16x32_bf16 v[110:113], v[150:153], v[166:169], v[110:113]
	v_mfma_f32_16x16x32_bf16 v[40:43], v[158:161], v[166:169], v[40:43]
	v_mfma_f32_16x16x32_bf16 v[106:109], v[150:153], v[178:181], v[106:109]
	v_mfma_f32_16x16x32_bf16 v[36:39], v[158:161], v[178:181], v[36:39]
	v_mfma_f32_16x16x32_bf16 v[102:105], v[150:153], v[206:209], v[102:105]
	v_mfma_f32_16x16x32_bf16 v[48:51], v[158:161], v[206:209], v[48:51]
	v_mfma_f32_16x16x32_bf16 v[98:101], v[150:153], v[230:233], v[98:101]
	v_mfma_f32_16x16x32_bf16 v[32:35], v[158:161], v[230:233], v[32:35]
	s_barrier
	s_setprio 0
	s_add_i32 s62, s67, s5
	v_lshl_add_u64 v[188:189], vcc, 0, v[96:97]
	s_mov_b32 m0, s62
	ds_read_b128 v[162:165], v224 offset:16384
	ds_read_b128 v[166:169], v224 offset:17408
	ds_read_b128 v[170:173], v224 offset:18432
	ds_read_b128 v[178:181], v224 offset:19456
	ds_read_b128 v[202:205], v224 offset:20480
	ds_read_b128 v[206:209], v224 offset:21504
	ds_read_b128 v[226:229], v224 offset:22528
	ds_read_b128 v[230:233], v224 offset:23552
	global_load_lds_dwordx4 v[188:189], off
	s_add_i32 m0, s62, 0x2000
	s_add_u32 s62, vcc_lo, 0x80000
	v_lshl_add_u64 v[198:199], vcc, 0, v[182:183]
	s_addc_u32 s63, vcc_hi, 0
	s_add_i32 s67, s76, s5
	global_load_lds_dwordx4 v[198:199], off
	v_lshl_add_u64 v[200:201], s[62:63], 0, v[96:97]
	s_mov_b32 m0, s67
	v_lshl_add_u64 v[234:235], s[88:89], 0, v[176:177]
	global_load_lds_dwordx4 v[200:201], off
	v_lshl_add_u64 v[200:201], s[62:63], 0, v[182:183]
	s_add_i32 m0, s67, 0x2000
	s_nop 0
	global_load_lds_dwordx4 v[200:201], off
	v_lshl_add_u64 v[200:201], s[88:89], 0, v[174:175]
	s_mov_b32 m0, s17
	s_nop 0
	global_load_lds_dwordx4 v[200:201], off
	s_mov_b32 m0, s18
	s_nop 0
	global_load_lds_dwordx4 v[234:235], off
	s_setprio 1
	s_waitcnt vmcnt(8)
	s_waitcnt lgkmcnt(0)
	s_barrier
	v_mfma_f32_16x16x32_bf16 v[92:95], v[130:133], v[162:165], v[92:95]
	v_mfma_f32_16x16x32_bf16 v[24:27], v[138:141], v[162:165], v[24:27]
	v_mfma_f32_16x16x32_bf16 v[88:91], v[130:133], v[170:173], v[88:91]
	v_mfma_f32_16x16x32_bf16 v[28:31], v[138:141], v[170:173], v[28:31]
	v_mfma_f32_16x16x32_bf16 v[84:87], v[130:133], v[202:205], v[84:87]
	v_mfma_f32_16x16x32_bf16 v[16:19], v[138:141], v[202:205], v[16:19]
	v_mfma_f32_16x16x32_bf16 v[80:83], v[130:133], v[226:229], v[80:83]
	v_mfma_f32_16x16x32_bf16 v[20:23], v[138:141], v[226:229], v[20:23]
	v_mfma_f32_16x16x32_bf16 v[92:95], v[134:137], v[166:169], v[92:95]
	v_mfma_f32_16x16x32_bf16 v[24:27], v[142:145], v[166:169], v[24:27]
	v_mfma_f32_16x16x32_bf16 v[88:91], v[134:137], v[178:181], v[88:91]
	v_mfma_f32_16x16x32_bf16 v[28:31], v[142:145], v[178:181], v[28:31]
	v_mfma_f32_16x16x32_bf16 v[84:87], v[134:137], v[206:209], v[84:87]
	v_mfma_f32_16x16x32_bf16 v[16:19], v[142:145], v[206:209], v[16:19]
	v_mfma_f32_16x16x32_bf16 v[80:83], v[134:137], v[230:233], v[80:83]
	v_mfma_f32_16x16x32_bf16 v[20:23], v[142:145], v[230:233], v[20:23]
	v_mfma_f32_16x16x32_bf16 v[76:79], v[146:149], v[162:165], v[76:79]
	v_mfma_f32_16x16x32_bf16 v[12:15], v[154:157], v[162:165], v[12:15]
	v_mfma_f32_16x16x32_bf16 v[72:75], v[146:149], v[170:173], v[72:75]
	v_mfma_f32_16x16x32_bf16 v[8:11], v[154:157], v[170:173], v[8:11]
	v_mfma_f32_16x16x32_bf16 v[68:71], v[146:149], v[202:205], v[68:71]
	v_mfma_f32_16x16x32_bf16 v[0:3], v[154:157], v[202:205], v[0:3]
	v_mfma_f32_16x16x32_bf16 v[64:67], v[146:149], v[226:229], v[64:67]
	v_mfma_f32_16x16x32_bf16 v[4:7], v[154:157], v[226:229], v[4:7]
	v_mfma_f32_16x16x32_bf16 v[76:79], v[150:153], v[166:169], v[76:79]
	v_mfma_f32_16x16x32_bf16 v[12:15], v[158:161], v[166:169], v[12:15]
	v_mfma_f32_16x16x32_bf16 v[72:75], v[150:153], v[178:181], v[72:75]
	v_mfma_f32_16x16x32_bf16 v[8:11], v[158:161], v[178:181], v[8:11]
	v_mfma_f32_16x16x32_bf16 v[68:71], v[150:153], v[206:209], v[68:71]
	v_mfma_f32_16x16x32_bf16 v[0:3], v[158:161], v[206:209], v[0:3]
	v_mfma_f32_16x16x32_bf16 v[64:67], v[150:153], v[230:233], v[64:67]
	v_mfma_f32_16x16x32_bf16 v[4:7], v[158:161], v[230:233], v[4:7]
	s_barrier
	s_setprio 0
	s_add_i32 s67, 0, 0x18000
	s_add_i32 s76, 0, 0x1c000
	v_add_u32_e32 v142, s67, v191
	v_add_u32_e32 v158, s76, v191
	ds_read_b128 v[130:133], v142
	ds_read_b128 v[134:137], v142 offset:1024
	ds_read_b128 v[138:141], v142 offset:2048
	ds_read_b128 v[142:145], v142 offset:3072
	ds_read_b128 v[146:149], v158
	ds_read_b128 v[150:153], v158 offset:1024
	ds_read_b128 v[154:157], v158 offset:2048
	ds_read_b128 v[158:161], v158 offset:3072
	s_add_u32 s62, s88, 0x80000
	s_addc_u32 s63, s89, 0
	s_mov_b32 m0, s19
	v_lshl_add_u64 v[236:237], s[62:63], 0, v[174:175]
	ds_read_b128 v[162:165], v224 offset:32768
	ds_read_b128 v[166:169], v224 offset:33792
	ds_read_b128 v[170:173], v224 offset:34816
	ds_read_b128 v[178:181], v224 offset:35840
	ds_read_b128 v[202:205], v224 offset:36864
	ds_read_b128 v[206:209], v224 offset:37888
	ds_read_b128 v[226:229], v224 offset:38912
	ds_read_b128 v[230:233], v224 offset:39936
	global_load_lds_dwordx4 v[236:237], off
	v_lshl_add_u64 v[236:237], s[62:63], 0, v[176:177]
	s_mov_b32 m0, s20
	s_nop 0
	global_load_lds_dwordx4 v[236:237], off
	s_setprio 1
	s_waitcnt vmcnt(8)
	s_waitcnt lgkmcnt(0)
	s_barrier
	v_mfma_f32_16x16x32_bf16 v[126:129], v[130:133], v[162:165], v[126:129]
	v_mfma_f32_16x16x32_bf16 v[56:59], v[138:141], v[162:165], v[56:59]
	v_mfma_f32_16x16x32_bf16 v[122:125], v[130:133], v[170:173], v[122:125]
	v_mfma_f32_16x16x32_bf16 v[52:55], v[138:141], v[170:173], v[52:55]
	v_mfma_f32_16x16x32_bf16 v[118:121], v[130:133], v[202:205], v[118:121]
	v_mfma_f32_16x16x32_bf16 v[60:63], v[138:141], v[202:205], v[60:63]
	v_mfma_f32_16x16x32_bf16 v[114:117], v[130:133], v[226:229], v[114:117]
	v_mfma_f32_16x16x32_bf16 v[44:47], v[138:141], v[226:229], v[44:47]
	v_mfma_f32_16x16x32_bf16 v[126:129], v[134:137], v[166:169], v[126:129]
	v_mfma_f32_16x16x32_bf16 v[56:59], v[142:145], v[166:169], v[56:59]
	v_mfma_f32_16x16x32_bf16 v[122:125], v[134:137], v[178:181], v[122:125]
	v_mfma_f32_16x16x32_bf16 v[52:55], v[142:145], v[178:181], v[52:55]
	v_mfma_f32_16x16x32_bf16 v[118:121], v[134:137], v[206:209], v[118:121]
	v_mfma_f32_16x16x32_bf16 v[60:63], v[142:145], v[206:209], v[60:63]
	v_mfma_f32_16x16x32_bf16 v[114:117], v[134:137], v[230:233], v[114:117]
	v_mfma_f32_16x16x32_bf16 v[44:47], v[142:145], v[230:233], v[44:47]
	v_mfma_f32_16x16x32_bf16 v[110:113], v[146:149], v[162:165], v[110:113]
	v_mfma_f32_16x16x32_bf16 v[40:43], v[154:157], v[162:165], v[40:43]
	v_mfma_f32_16x16x32_bf16 v[106:109], v[146:149], v[170:173], v[106:109]
	v_mfma_f32_16x16x32_bf16 v[36:39], v[154:157], v[170:173], v[36:39]
	v_mfma_f32_16x16x32_bf16 v[102:105], v[146:149], v[202:205], v[102:105]
	v_mfma_f32_16x16x32_bf16 v[48:51], v[154:157], v[202:205], v[48:51]
	v_mfma_f32_16x16x32_bf16 v[98:101], v[146:149], v[226:229], v[98:101]
	v_mfma_f32_16x16x32_bf16 v[32:35], v[154:157], v[226:229], v[32:35]
	v_mfma_f32_16x16x32_bf16 v[110:113], v[150:153], v[166:169], v[110:113]
	v_mfma_f32_16x16x32_bf16 v[40:43], v[158:161], v[166:169], v[40:43]
	v_mfma_f32_16x16x32_bf16 v[106:109], v[150:153], v[178:181], v[106:109]
	v_mfma_f32_16x16x32_bf16 v[36:39], v[158:161], v[178:181], v[36:39]
	v_mfma_f32_16x16x32_bf16 v[102:105], v[150:153], v[206:209], v[102:105]
	v_mfma_f32_16x16x32_bf16 v[48:51], v[158:161], v[206:209], v[48:51]
	v_mfma_f32_16x16x32_bf16 v[98:101], v[150:153], v[230:233], v[98:101]
	v_mfma_f32_16x16x32_bf16 v[32:35], v[158:161], v[230:233], v[32:35]
	s_barrier
	s_setprio 0
	s_add_i32 s62, s67, s5
	v_lshl_add_u64 v[188:189], v[188:189], 0, s[30:31]
	s_mov_b32 m0, s62
	ds_read_b128 v[162:165], v224 offset:49152
	ds_read_b128 v[166:169], v224 offset:50176
	ds_read_b128 v[170:173], v224 offset:51200
	ds_read_b128 v[178:181], v224 offset:52224
	ds_read_b128 v[202:205], v224 offset:53248
	ds_read_b128 v[206:209], v224 offset:54272
	ds_read_b128 v[226:229], v224 offset:55296
	ds_read_b128 v[230:233], v224 offset:56320
	global_load_lds_dwordx4 v[188:189], off
	s_add_i32 m0, s62, 0x2000
	s_add_u32 s62, vcc_lo, 0x80080
	v_lshl_add_u64 v[188:189], v[198:199], 0, s[30:31]
	s_addc_u32 s63, vcc_hi, 0
	s_add_i32 s67, s76, s5
	global_load_lds_dwordx4 v[188:189], off
	v_lshl_add_u64 v[188:189], s[62:63], 0, v[96:97]
	s_mov_b32 m0, s67
	s_nop 0
	global_load_lds_dwordx4 v[188:189], off
	v_lshl_add_u64 v[188:189], s[62:63], 0, v[182:183]
	s_add_i32 m0, s67, 0x2000
	s_nop 0
	global_load_lds_dwordx4 v[188:189], off
	v_lshl_add_u64 v[188:189], v[200:201], 0, s[30:31]
	s_mov_b32 m0, s36
	s_nop 0
	global_load_lds_dwordx4 v[188:189], off
	v_lshl_add_u64 v[188:189], v[234:235], 0, s[30:31]
	s_mov_b32 m0, s37
	s_nop 0
	global_load_lds_dwordx4 v[188:189], off
	s_setprio 1
	s_waitcnt vmcnt(8)
	s_waitcnt lgkmcnt(0)
	s_barrier
	v_mfma_f32_16x16x32_bf16 v[92:95], v[130:133], v[162:165], v[92:95]
	v_mfma_f32_16x16x32_bf16 v[24:27], v[138:141], v[162:165], v[24:27]
	v_mfma_f32_16x16x32_bf16 v[88:91], v[130:133], v[170:173], v[88:91]
	v_mfma_f32_16x16x32_bf16 v[28:31], v[138:141], v[170:173], v[28:31]
	v_mfma_f32_16x16x32_bf16 v[84:87], v[130:133], v[202:205], v[84:87]
	v_mfma_f32_16x16x32_bf16 v[16:19], v[138:141], v[202:205], v[16:19]
	v_mfma_f32_16x16x32_bf16 v[80:83], v[130:133], v[226:229], v[80:83]
	v_mfma_f32_16x16x32_bf16 v[20:23], v[138:141], v[226:229], v[20:23]
	v_mfma_f32_16x16x32_bf16 v[92:95], v[134:137], v[166:169], v[92:95]
	v_mfma_f32_16x16x32_bf16 v[24:27], v[142:145], v[166:169], v[24:27]
	v_mfma_f32_16x16x32_bf16 v[88:91], v[134:137], v[178:181], v[88:91]
	v_mfma_f32_16x16x32_bf16 v[28:31], v[142:145], v[178:181], v[28:31]
	v_mfma_f32_16x16x32_bf16 v[84:87], v[134:137], v[206:209], v[84:87]
	v_mfma_f32_16x16x32_bf16 v[16:19], v[142:145], v[206:209], v[16:19]
	v_mfma_f32_16x16x32_bf16 v[80:83], v[134:137], v[230:233], v[80:83]
	v_mfma_f32_16x16x32_bf16 v[20:23], v[142:145], v[230:233], v[20:23]
	v_mfma_f32_16x16x32_bf16 v[76:79], v[146:149], v[162:165], v[76:79]
	v_mfma_f32_16x16x32_bf16 v[12:15], v[154:157], v[162:165], v[12:15]
	v_mfma_f32_16x16x32_bf16 v[72:75], v[146:149], v[170:173], v[72:75]
	v_mfma_f32_16x16x32_bf16 v[8:11], v[154:157], v[170:173], v[8:11]
	v_mfma_f32_16x16x32_bf16 v[68:71], v[146:149], v[202:205], v[68:71]
	v_mfma_f32_16x16x32_bf16 v[0:3], v[154:157], v[202:205], v[0:3]
	v_mfma_f32_16x16x32_bf16 v[64:67], v[146:149], v[226:229], v[64:67]
	v_mfma_f32_16x16x32_bf16 v[4:7], v[154:157], v[226:229], v[4:7]
	v_mfma_f32_16x16x32_bf16 v[76:79], v[150:153], v[166:169], v[76:79]
	v_mfma_f32_16x16x32_bf16 v[12:15], v[158:161], v[166:169], v[12:15]
	v_mfma_f32_16x16x32_bf16 v[72:75], v[150:153], v[178:181], v[72:75]
	v_mfma_f32_16x16x32_bf16 v[8:11], v[158:161], v[178:181], v[8:11]
	v_mfma_f32_16x16x32_bf16 v[68:71], v[150:153], v[206:209], v[68:71]
	v_mfma_f32_16x16x32_bf16 v[0:3], v[158:161], v[206:209], v[0:3]
	v_mfma_f32_16x16x32_bf16 v[64:67], v[150:153], v[230:233], v[64:67]
	v_mfma_f32_16x16x32_bf16 v[4:7], v[158:161], v[230:233], v[4:7]
	s_barrier
	s_setprio 0
	s_add_i32 s6, s6, 2
	s_add_u32 s2, s2, 0x100
	s_addc_u32 s3, s3, 0
	s_cmp_gt_u32 s6, 29
	s_mov_b64 s[62:63], s[34:35]
	s_cbranch_scc0 .LBB0_1158
	s_nop 0
	s_nop 0
	s_nop 0
	s_nop 0
	s_nop 0
	s_nop 0
	s_nop 0
	s_nop 0
	s_nop 0
	s_nop 0
	s_nop 0
	s_nop 0
	s_and_b64 vcc, exec, s[24:25]
	s_cbranch_vccz .LBB0_1161
	s_barrier

.LBB0_1333:
	s_add_u32 s38, s42, 0x100
	s_addc_u32 s39, s43, 0
	s_add_i32 s13, 0, 0x10000
	s_cmp_eq_u32 s6, 4
	s_cselect_b32 s47, s25, s39
	s_cselect_b32 s46, s24, s38
	s_cselect_b32 s45, s35, s3
	s_cselect_b32 s44, s34, s2
	s_add_i32 s23, 0, 0x14000
	v_add_u32_e32 v152, s13, v136
	v_add_u32_e32 v168, s23, v136
	ds_read_b128 v[140:143], v152
	ds_read_b128 v[144:147], v152 offset:1024
	ds_read_b128 v[148:151], v152 offset:2048
	ds_read_b128 v[152:155], v152 offset:3072
	ds_read_b128 v[156:159], v168
	ds_read_b128 v[160:163], v168 offset:1024
	ds_read_b128 v[164:167], v168 offset:2048
	ds_read_b128 v[168:171], v168 offset:3072
	v_lshl_add_u64 v[198:199], s[42:43], 0, v[132:133]
	s_add_i32 m0, s5, 0xc000
	ds_read_b128 v[172:175], v139
	ds_read_b128 v[176:179], v139 offset:1024
	ds_read_b128 v[180:183], v139 offset:2048
	ds_read_b128 v[184:187], v139 offset:3072
	ds_read_b128 v[188:191], v139 offset:4096
	ds_read_b128 v[192:195], v139 offset:5120
	ds_read_b128 v[202:205], v139 offset:6144
	ds_read_b128 v[206:209], v139 offset:7168
	global_load_lds_dwordx4 v[198:199], off
	v_lshl_add_u64 v[198:199], s[42:43], 0, v[134:135]
	s_add_i32 m0, s5, 0xe000
	s_nop 0
	global_load_lds_dwordx4 v[198:199], off
	s_setprio 1
	s_waitcnt vmcnt(8)
	s_waitcnt lgkmcnt(0)
	s_barrier
	v_mfma_f32_16x16x32_bf16 v[126:129], v[140:143], v[172:175], v[126:129]
	v_mfma_f32_16x16x32_bf16 v[122:125], v[148:151], v[172:175], v[122:125]
	v_mfma_f32_16x16x32_bf16 v[118:121], v[140:143], v[180:183], v[118:121]
	v_mfma_f32_16x16x32_bf16 v[114:117], v[148:151], v[180:183], v[114:117]
	v_mfma_f32_16x16x32_bf16 v[106:109], v[140:143], v[188:191], v[106:109]
	v_mfma_f32_16x16x32_bf16 v[98:101], v[148:151], v[188:191], v[98:101]
	v_mfma_f32_16x16x32_bf16 v[88:91], v[140:143], v[202:205], v[88:91]
	v_mfma_f32_16x16x32_bf16 v[80:83], v[148:151], v[202:205], v[80:83]
	v_mfma_f32_16x16x32_bf16 v[126:129], v[144:147], v[176:179], v[126:129]
	v_mfma_f32_16x16x32_bf16 v[122:125], v[152:155], v[176:179], v[122:125]
	v_mfma_f32_16x16x32_bf16 v[118:121], v[144:147], v[184:187], v[118:121]
	v_mfma_f32_16x16x32_bf16 v[114:117], v[152:155], v[184:187], v[114:117]
	v_mfma_f32_16x16x32_bf16 v[106:109], v[144:147], v[192:195], v[106:109]
	v_mfma_f32_16x16x32_bf16 v[98:101], v[152:155], v[192:195], v[98:101]
	v_mfma_f32_16x16x32_bf16 v[88:91], v[144:147], v[206:209], v[88:91]
	v_mfma_f32_16x16x32_bf16 v[80:83], v[152:155], v[206:209], v[80:83]
	v_mfma_f32_16x16x32_bf16 v[110:113], v[156:159], v[172:175], v[110:113]
	v_mfma_f32_16x16x32_bf16 v[102:105], v[164:167], v[172:175], v[102:105]
	v_mfma_f32_16x16x32_bf16 v[92:95], v[156:159], v[180:183], v[92:95]
	v_mfma_f32_16x16x32_bf16 v[84:87], v[164:167], v[180:183], v[84:87]
	v_mfma_f32_16x16x32_bf16 v[76:79], v[156:159], v[188:191], v[76:79]
	v_mfma_f32_16x16x32_bf16 v[72:75], v[164:167], v[188:191], v[72:75]
	v_mfma_f32_16x16x32_bf16 v[68:71], v[156:159], v[202:205], v[68:71]
	v_mfma_f32_16x16x32_bf16 v[64:67], v[164:167], v[202:205], v[64:67]
	v_mfma_f32_16x16x32_bf16 v[110:113], v[160:163], v[176:179], v[110:113]
	v_mfma_f32_16x16x32_bf16 v[102:105], v[168:171], v[176:179], v[102:105]
	v_mfma_f32_16x16x32_bf16 v[92:95], v[160:163], v[184:187], v[92:95]
	v_mfma_f32_16x16x32_bf16 v[84:87], v[168:171], v[184:187], v[84:87]
	v_mfma_f32_16x16x32_bf16 v[76:79], v[160:163], v[192:195], v[76:79]
	v_mfma_f32_16x16x32_bf16 v[72:75], v[168:171], v[192:195], v[72:75]
	v_mfma_f32_16x16x32_bf16 v[68:71], v[160:163], v[206:209], v[68:71]
	v_mfma_f32_16x16x32_bf16 v[64:67], v[168:171], v[206:209], v[64:67]
	s_barrier
	s_setprio 0
	s_add_i32 s13, s13, s4
	v_lshl_add_u64 v[198:199], s[44:45], 0, v[96:97]
	s_mov_b32 m0, s13
	ds_read_b128 v[172:175], v139 offset:16384
	ds_read_b128 v[176:179], v139 offset:17408
	ds_read_b128 v[180:183], v139 offset:18432
	ds_read_b128 v[184:187], v139 offset:19456
	ds_read_b128 v[188:191], v139 offset:20480
	ds_read_b128 v[192:195], v139 offset:21504
	ds_read_b128 v[202:205], v139 offset:22528
	ds_read_b128 v[206:209], v139 offset:23552
	global_load_lds_dwordx4 v[198:199], off
	s_add_i32 m0, s13, 0x2000
	s_add_u32 s42, s44, 0x160000
	v_lshl_add_u64 v[200:201], s[44:45], 0, v[130:131]
	s_addc_u32 s43, s45, 0
	s_add_i32 s13, s23, s4
	global_load_lds_dwordx4 v[200:201], off
	v_lshl_add_u64 v[214:215], s[42:43], 0, v[96:97]
	s_mov_b32 m0, s13
	v_lshl_add_u64 v[216:217], s[46:47], 0, v[130:131]
	global_load_lds_dwordx4 v[214:215], off
	v_lshl_add_u64 v[214:215], s[42:43], 0, v[130:131]
	s_add_i32 m0, s13, 0x2000
	s_nop 0
	global_load_lds_dwordx4 v[214:215], off
	v_lshl_add_u64 v[214:215], s[46:47], 0, v[96:97]
	s_mov_b32 m0, s5
	s_nop 0
	global_load_lds_dwordx4 v[214:215], off
	s_mov_b32 m0, s17
	s_nop 0
	global_load_lds_dwordx4 v[216:217], off
	s_setprio 1
	s_waitcnt vmcnt(8)
	s_waitcnt lgkmcnt(0)
	s_barrier
	v_mfma_f32_16x16x32_bf16 v[60:63], v[140:143], v[172:175], v[60:63]
	v_mfma_f32_16x16x32_bf16 v[56:59], v[148:151], v[172:175], v[56:59]
	v_mfma_f32_16x16x32_bf16 v[52:55], v[140:143], v[180:183], v[52:55]
	v_mfma_f32_16x16x32_bf16 v[48:51], v[148:151], v[180:183], v[48:51]
	v_mfma_f32_16x16x32_bf16 v[36:39], v[140:143], v[188:191], v[36:39]
	v_mfma_f32_16x16x32_bf16 v[32:35], v[148:151], v[188:191], v[32:35]
	v_mfma_f32_16x16x32_bf16 v[20:23], v[140:143], v[202:205], v[20:23]
	v_mfma_f32_16x16x32_bf16 v[16:19], v[148:151], v[202:205], v[16:19]
	v_mfma_f32_16x16x32_bf16 v[60:63], v[144:147], v[176:179], v[60:63]
	v_mfma_f32_16x16x32_bf16 v[56:59], v[152:155], v[176:179], v[56:59]
	v_mfma_f32_16x16x32_bf16 v[52:55], v[144:147], v[184:187], v[52:55]
	v_mfma_f32_16x16x32_bf16 v[48:51], v[152:155], v[184:187], v[48:51]
	v_mfma_f32_16x16x32_bf16 v[36:39], v[144:147], v[192:195], v[36:39]
	v_mfma_f32_16x16x32_bf16 v[32:35], v[152:155], v[192:195], v[32:35]
	v_mfma_f32_16x16x32_bf16 v[20:23], v[144:147], v[206:209], v[20:23]
	v_mfma_f32_16x16x32_bf16 v[16:19], v[152:155], v[206:209], v[16:19]
	v_mfma_f32_16x16x32_bf16 v[44:47], v[156:159], v[172:175], v[44:47]
	v_mfma_f32_16x16x32_bf16 v[40:43], v[164:167], v[172:175], v[40:43]
	v_mfma_f32_16x16x32_bf16 v[28:31], v[156:159], v[180:183], v[28:31]
	v_mfma_f32_16x16x32_bf16 v[24:27], v[164:167], v[180:183], v[24:27]
	v_mfma_f32_16x16x32_bf16 v[12:15], v[156:159], v[188:191], v[12:15]
	v_mfma_f32_16x16x32_bf16 v[8:11], v[164:167], v[188:191], v[8:11]
	v_mfma_f32_16x16x32_bf16 v[4:7], v[156:159], v[202:205], v[4:7]
	v_mfma_f32_16x16x32_bf16 v[0:3], v[164:167], v[202:205], v[0:3]
	v_mfma_f32_16x16x32_bf16 v[44:47], v[160:163], v[176:179], v[44:47]
	v_mfma_f32_16x16x32_bf16 v[40:43], v[168:171], v[176:179], v[40:43]
	v_mfma_f32_16x16x32_bf16 v[28:31], v[160:163], v[184:187], v[28:31]
	v_mfma_f32_16x16x32_bf16 v[24:27], v[168:171], v[184:187], v[24:27]
	v_mfma_f32_16x16x32_bf16 v[12:15], v[160:163], v[192:195], v[12:15]
	v_mfma_f32_16x16x32_bf16 v[8:11], v[168:171], v[192:195], v[8:11]
	v_mfma_f32_16x16x32_bf16 v[4:7], v[160:163], v[206:209], v[4:7]
	v_mfma_f32_16x16x32_bf16 v[0:3], v[168:171], v[206:209], v[0:3]
	s_barrier
	s_setprio 0
	s_add_i32 s13, 0, 0x18000
	s_add_i32 s23, 0, 0x1c000
	v_add_u32_e32 v152, s13, v136
	v_add_u32_e32 v168, s23, v136
	ds_read_b128 v[140:143], v152
	ds_read_b128 v[144:147], v152 offset:1024
	ds_read_b128 v[148:151], v152 offset:2048
	ds_read_b128 v[152:155], v152 offset:3072
	ds_read_b128 v[156:159], v168
	ds_read_b128 v[160:163], v168 offset:1024
	ds_read_b128 v[164:167], v168 offset:2048
	ds_read_b128 v[168:171], v168 offset:3072
	s_add_u32 s42, s46, 0x160000
	s_addc_u32 s43, s47, 0
	s_mov_b32 m0, s18
	v_lshl_add_u64 v[218:219], s[42:43], 0, v[96:97]
	ds_read_b128 v[172:175], v139 offset:32768
	ds_read_b128 v[176:179], v139 offset:33792
	ds_read_b128 v[180:183], v139 offset:34816
	ds_read_b128 v[184:187], v139 offset:35840
	ds_read_b128 v[188:191], v139 offset:36864
	ds_read_b128 v[192:195], v139 offset:37888
	ds_read_b128 v[202:205], v139 offset:38912
	ds_read_b128 v[206:209], v139 offset:39936
	global_load_lds_dwordx4 v[218:219], off
	v_lshl_add_u64 v[218:219], s[42:43], 0, v[130:131]
	s_mov_b32 m0, s19
	s_nop 0
	global_load_lds_dwordx4 v[218:219], off
	s_setprio 1
	s_waitcnt vmcnt(8)
	s_waitcnt lgkmcnt(0)
	s_barrier
	v_mfma_f32_16x16x32_bf16 v[126:129], v[140:143], v[172:175], v[126:129]
	v_mfma_f32_16x16x32_bf16 v[122:125], v[148:151], v[172:175], v[122:125]
	v_mfma_f32_16x16x32_bf16 v[118:121], v[140:143], v[180:183], v[118:121]
	v_mfma_f32_16x16x32_bf16 v[114:117], v[148:151], v[180:183], v[114:117]
	v_mfma_f32_16x16x32_bf16 v[106:109], v[140:143], v[188:191], v[106:109]
	v_mfma_f32_16x16x32_bf16 v[98:101], v[148:151], v[188:191], v[98:101]
	v_mfma_f32_16x16x32_bf16 v[88:91], v[140:143], v[202:205], v[88:91]
	v_mfma_f32_16x16x32_bf16 v[80:83], v[148:151], v[202:205], v[80:83]
	v_mfma_f32_16x16x32_bf16 v[126:129], v[144:147], v[176:179], v[126:129]
	v_mfma_f32_16x16x32_bf16 v[122:125], v[152:155], v[176:179], v[122:125]
	v_mfma_f32_16x16x32_bf16 v[118:121], v[144:147], v[184:187], v[118:121]
	v_mfma_f32_16x16x32_bf16 v[114:117], v[152:155], v[184:187], v[114:117]
	v_mfma_f32_16x16x32_bf16 v[106:109], v[144:147], v[192:195], v[106:109]
	v_mfma_f32_16x16x32_bf16 v[98:101], v[152:155], v[192:195], v[98:101]
	v_mfma_f32_16x16x32_bf16 v[88:91], v[144:147], v[206:209], v[88:91]
	v_mfma_f32_16x16x32_bf16 v[80:83], v[152:155], v[206:209], v[80:83]
	v_mfma_f32_16x16x32_bf16 v[110:113], v[156:159], v[172:175], v[110:113]
	v_mfma_f32_16x16x32_bf16 v[102:105], v[164:167], v[172:175], v[102:105]
	v_mfma_f32_16x16x32_bf16 v[92:95], v[156:159], v[180:183], v[92:95]
	v_mfma_f32_16x16x32_bf16 v[84:87], v[164:167], v[180:183], v[84:87]
	v_mfma_f32_16x16x32_bf16 v[76:79], v[156:159], v[188:191], v[76:79]
	v_mfma_f32_16x16x32_bf16 v[72:75], v[164:167], v[188:191], v[72:75]
	v_mfma_f32_16x16x32_bf16 v[68:71], v[156:159], v[202:205], v[68:71]
	v_mfma_f32_16x16x32_bf16 v[64:67], v[164:167], v[202:205], v[64:67]
	v_mfma_f32_16x16x32_bf16 v[110:113], v[160:163], v[176:179], v[110:113]
	v_mfma_f32_16x16x32_bf16 v[102:105], v[168:171], v[176:179], v[102:105]
	v_mfma_f32_16x16x32_bf16 v[92:95], v[160:163], v[184:187], v[92:95]
	v_mfma_f32_16x16x32_bf16 v[84:87], v[168:171], v[184:187], v[84:87]
	v_mfma_f32_16x16x32_bf16 v[76:79], v[160:163], v[192:195], v[76:79]
	v_mfma_f32_16x16x32_bf16 v[72:75], v[168:171], v[192:195], v[72:75]
	v_mfma_f32_16x16x32_bf16 v[68:71], v[160:163], v[206:209], v[68:71]
	v_mfma_f32_16x16x32_bf16 v[64:67], v[168:171], v[206:209], v[64:67]
	s_barrier
	s_setprio 0
	s_add_i32 s13, s13, s4
	v_lshl_add_u64 v[198:199], v[198:199], 0, s[30:31]
	s_mov_b32 m0, s13
	ds_read_b128 v[172:175], v139 offset:49152
	ds_read_b128 v[176:179], v139 offset:50176
	ds_read_b128 v[180:183], v139 offset:51200
	ds_read_b128 v[184:187], v139 offset:52224
	ds_read_b128 v[188:191], v139 offset:53248
	ds_read_b128 v[192:195], v139 offset:54272
	ds_read_b128 v[202:205], v139 offset:55296
	ds_read_b128 v[206:209], v139 offset:56320
	global_load_lds_dwordx4 v[198:199], off
	s_add_i32 m0, s13, 0x2000
	s_add_u32 s42, s44, 0x160080
	v_lshl_add_u64 v[198:199], v[200:201], 0, s[30:31]
	s_addc_u32 s43, s45, 0
	s_add_i32 s13, s23, s4
	global_load_lds_dwordx4 v[198:199], off
	v_lshl_add_u64 v[198:199], s[42:43], 0, v[96:97]
	s_mov_b32 m0, s13
	s_nop 0
	global_load_lds_dwordx4 v[198:199], off
	v_lshl_add_u64 v[198:199], s[42:43], 0, v[130:131]
	s_add_i32 m0, s13, 0x2000
	s_nop 0
	global_load_lds_dwordx4 v[198:199], off
	v_lshl_add_u64 v[198:199], v[214:215], 0, s[30:31]
	s_mov_b32 m0, s37
	s_nop 0
	global_load_lds_dwordx4 v[198:199], off
	v_lshl_add_u64 v[198:199], v[216:217], 0, s[30:31]
	s_mov_b32 m0, s40
	s_nop 0
	global_load_lds_dwordx4 v[198:199], off
	s_setprio 1
	s_waitcnt vmcnt(8)
	s_waitcnt lgkmcnt(0)
	s_barrier
	v_mfma_f32_16x16x32_bf16 v[60:63], v[140:143], v[172:175], v[60:63]
	v_mfma_f32_16x16x32_bf16 v[56:59], v[148:151], v[172:175], v[56:59]
	v_mfma_f32_16x16x32_bf16 v[52:55], v[140:143], v[180:183], v[52:55]
	v_mfma_f32_16x16x32_bf16 v[48:51], v[148:151], v[180:183], v[48:51]
	v_mfma_f32_16x16x32_bf16 v[36:39], v[140:143], v[188:191], v[36:39]
	v_mfma_f32_16x16x32_bf16 v[32:35], v[148:151], v[188:191], v[32:35]
	v_mfma_f32_16x16x32_bf16 v[20:23], v[140:143], v[202:205], v[20:23]
	v_mfma_f32_16x16x32_bf16 v[16:19], v[148:151], v[202:205], v[16:19]
	v_mfma_f32_16x16x32_bf16 v[60:63], v[144:147], v[176:179], v[60:63]
	v_mfma_f32_16x16x32_bf16 v[56:59], v[152:155], v[176:179], v[56:59]
	v_mfma_f32_16x16x32_bf16 v[52:55], v[144:147], v[184:187], v[52:55]
	v_mfma_f32_16x16x32_bf16 v[48:51], v[152:155], v[184:187], v[48:51]
	v_mfma_f32_16x16x32_bf16 v[36:39], v[144:147], v[192:195], v[36:39]
	v_mfma_f32_16x16x32_bf16 v[32:35], v[152:155], v[192:195], v[32:35]
	v_mfma_f32_16x16x32_bf16 v[20:23], v[144:147], v[206:209], v[20:23]
	v_mfma_f32_16x16x32_bf16 v[16:19], v[152:155], v[206:209], v[16:19]
	v_mfma_f32_16x16x32_bf16 v[44:47], v[156:159], v[172:175], v[44:47]
	v_mfma_f32_16x16x32_bf16 v[40:43], v[164:167], v[172:175], v[40:43]
	v_mfma_f32_16x16x32_bf16 v[28:31], v[156:159], v[180:183], v[28:31]
	v_mfma_f32_16x16x32_bf16 v[24:27], v[164:167], v[180:183], v[24:27]
	v_mfma_f32_16x16x32_bf16 v[12:15], v[156:159], v[188:191], v[12:15]
	v_mfma_f32_16x16x32_bf16 v[8:11], v[164:167], v[188:191], v[8:11]
	v_mfma_f32_16x16x32_bf16 v[4:7], v[156:159], v[202:205], v[4:7]
	v_mfma_f32_16x16x32_bf16 v[0:3], v[164:167], v[202:205], v[0:3]
	v_mfma_f32_16x16x32_bf16 v[44:47], v[160:163], v[176:179], v[44:47]
	v_mfma_f32_16x16x32_bf16 v[40:43], v[168:171], v[176:179], v[40:43]
	v_mfma_f32_16x16x32_bf16 v[28:31], v[160:163], v[184:187], v[28:31]
	v_mfma_f32_16x16x32_bf16 v[24:27], v[168:171], v[184:187], v[24:27]
	v_mfma_f32_16x16x32_bf16 v[12:15], v[160:163], v[192:195], v[12:15]
	v_mfma_f32_16x16x32_bf16 v[8:11], v[168:171], v[192:195], v[8:11]
	v_mfma_f32_16x16x32_bf16 v[4:7], v[160:163], v[206:209], v[4:7]
	v_mfma_f32_16x16x32_bf16 v[0:3], v[168:171], v[206:209], v[0:3]
	s_barrier
	s_setprio 0
	s_add_i32 s6, s6, 2
	s_add_u32 s2, s2, 0x100
	s_addc_u32 s3, s3, 0
	s_cmp_gt_u32 s6, 5
	s_mov_b64 s[42:43], s[38:39]
	s_cbranch_scc0 .LBB0_1333
	s_nop 0
	s_nop 0
	s_nop 0
	s_nop 0
	s_nop 0
	s_nop 0
	s_nop 0
	s_nop 0
	s_nop 0
	s_nop 0
	s_nop 0
	s_nop 0
	s_and_b64 vcc, exec, s[14:15]
	s_cbranch_vccz .LBB0_1336
	s_barrier

.LBB0_1357:
	s_add_u32 s3, s14, s34
	s_addc_u32 s6, s15, s35
	s_add_u32 s3, s3, 0x100
	s_addc_u32 s6, s6, 0
	s_add_u32 s42, s57, s34
	s_addc_u32 s43, s58, s35
	s_add_i32 s59, 0, 0x10000
	s_cmpk_eq_i32 s34, 0x2b00
	s_cselect_b32 s45, s23, s6
	s_cselect_b32 s44, s22, s3
	v_add_u32_e32 v146, s59, v144
	s_cselect_b32 s43, s25, s43
	s_cselect_b32 s42, s24, s42
	s_add_i32 s3, 0, 0x14000
	ds_read_b128 v[154:157], v146
	ds_read_b128 v[158:161], v146 offset:1024
	ds_read_b128 v[162:165], v146 offset:2048
	ds_read_b128 v[166:169], v146 offset:3072
	v_add_u32_e32 v146, s3, v144
	ds_read_b128 v[174:177], v146
	ds_read_b128 v[178:181], v146 offset:1024
	ds_read_b128 v[182:185], v146 offset:2048
	ds_read_b128 v[186:189], v146 offset:3072
	v_lshl_add_u64 v[146:147], v[140:141], 0, s[34:35]
	s_add_i32 m0, s17, 0xc000
	ds_read_b128 v[190:193], v145
	ds_read_b128 v[202:205], v145 offset:1024
	ds_read_b128 v[206:209], v145 offset:2048
	ds_read_b128 v[214:217], v145 offset:3072
	ds_read_b128 v[218:221], v145 offset:4096
	ds_read_b128 v[222:225], v145 offset:5120
	ds_read_b128 v[226:229], v145 offset:6144
	ds_read_b128 v[230:233], v145 offset:7168
	global_load_lds_dwordx4 v[146:147], off
	v_lshl_add_u64 v[146:147], v[142:143], 0, s[34:35]
	s_add_i32 m0, s17, 0xe000
	s_nop 0
	global_load_lds_dwordx4 v[146:147], off
	s_setprio 1
	s_waitcnt vmcnt(8)
	s_waitcnt lgkmcnt(0)
	s_barrier
	v_mfma_f32_16x16x32_bf16 v[110:113], v[154:157], v[190:193], v[110:113]
	v_mfma_f32_16x16x32_bf16 v[106:109], v[162:165], v[190:193], v[106:109]
	v_mfma_f32_16x16x32_bf16 v[118:121], v[154:157], v[206:209], v[118:121]
	v_mfma_f32_16x16x32_bf16 v[114:117], v[162:165], v[206:209], v[114:117]
	v_mfma_f32_16x16x32_bf16 v[126:129], v[154:157], v[218:221], v[126:129]
	v_mfma_f32_16x16x32_bf16 v[122:125], v[162:165], v[218:221], v[122:125]
	v_mfma_f32_16x16x32_bf16 v[92:95], v[154:157], v[226:229], v[92:95]
	v_mfma_f32_16x16x32_bf16 v[88:91], v[162:165], v[226:229], v[88:91]
	v_mfma_f32_16x16x32_bf16 v[110:113], v[158:161], v[202:205], v[110:113]
	v_mfma_f32_16x16x32_bf16 v[106:109], v[166:169], v[202:205], v[106:109]
	v_mfma_f32_16x16x32_bf16 v[118:121], v[158:161], v[214:217], v[118:121]
	v_mfma_f32_16x16x32_bf16 v[114:117], v[166:169], v[214:217], v[114:117]
	v_mfma_f32_16x16x32_bf16 v[126:129], v[158:161], v[222:225], v[126:129]
	v_mfma_f32_16x16x32_bf16 v[122:125], v[166:169], v[222:225], v[122:125]
	v_mfma_f32_16x16x32_bf16 v[92:95], v[158:161], v[230:233], v[92:95]
	v_mfma_f32_16x16x32_bf16 v[88:91], v[166:169], v[230:233], v[88:91]
	v_mfma_f32_16x16x32_bf16 v[4:7], v[174:177], v[190:193], v[4:7]
	v_mfma_f32_16x16x32_bf16 v[0:3], v[182:185], v[190:193], v[0:3]
	v_mfma_f32_16x16x32_bf16 v[12:15], v[174:177], v[206:209], v[12:15]
	v_mfma_f32_16x16x32_bf16 v[8:11], v[182:185], v[206:209], v[8:11]
	v_mfma_f32_16x16x32_bf16 v[24:27], v[174:177], v[218:221], v[24:27]
	v_mfma_f32_16x16x32_bf16 v[20:23], v[182:185], v[218:221], v[20:23]
	v_mfma_f32_16x16x32_bf16 v[40:43], v[174:177], v[226:229], v[40:43]
	v_mfma_f32_16x16x32_bf16 v[36:39], v[182:185], v[226:229], v[36:39]
	v_mfma_f32_16x16x32_bf16 v[4:7], v[178:181], v[202:205], v[4:7]
	v_mfma_f32_16x16x32_bf16 v[0:3], v[186:189], v[202:205], v[0:3]
	v_mfma_f32_16x16x32_bf16 v[12:15], v[178:181], v[214:217], v[12:15]
	v_mfma_f32_16x16x32_bf16 v[8:11], v[186:189], v[214:217], v[8:11]
	v_mfma_f32_16x16x32_bf16 v[24:27], v[178:181], v[222:225], v[24:27]
	v_mfma_f32_16x16x32_bf16 v[20:23], v[186:189], v[222:225], v[20:23]
	v_mfma_f32_16x16x32_bf16 v[40:43], v[178:181], v[230:233], v[40:43]
	v_mfma_f32_16x16x32_bf16 v[36:39], v[186:189], v[230:233], v[36:39]
	s_barrier
	s_setprio 0
	s_add_i32 s6, s59, s5
	v_lshl_add_u64 v[146:147], s[42:43], 0, v[96:97]
	s_mov_b32 m0, s6
	ds_read_b128 v[190:193], v145 offset:16384
	ds_read_b128 v[202:205], v145 offset:17408
	ds_read_b128 v[206:209], v145 offset:18432
	ds_read_b128 v[214:217], v145 offset:19456
	ds_read_b128 v[218:221], v145 offset:20480
	ds_read_b128 v[222:225], v145 offset:21504
	ds_read_b128 v[226:229], v145 offset:22528
	ds_read_b128 v[230:233], v145 offset:23552
	global_load_lds_dwordx4 v[146:147], off
	s_add_i32 m0, s6, 0x2000
	s_add_u32 s60, s42, 0x160000
	v_lshl_add_u64 v[150:151], s[42:43], 0, v[130:131]
	s_addc_u32 s61, s43, 0
	s_add_i32 s3, s3, s5
	global_load_lds_dwordx4 v[150:151], off
	v_lshl_add_u64 v[170:171], s[60:61], 0, v[96:97]
	s_mov_b32 m0, s3
	v_lshl_add_u64 v[194:195], s[44:45], 0, v[132:133]
	global_load_lds_dwordx4 v[170:171], off
	v_lshl_add_u64 v[170:171], s[60:61], 0, v[130:131]
	s_add_i32 m0, s3, 0x2000
	s_nop 0
	global_load_lds_dwordx4 v[170:171], off
	v_lshl_add_u64 v[170:171], s[44:45], 0, v[134:135]
	s_mov_b32 m0, s17
	s_nop 0
	global_load_lds_dwordx4 v[170:171], off
	s_mov_b32 m0, s18
	s_nop 0
	global_load_lds_dwordx4 v[194:195], off
	s_setprio 1
	s_waitcnt vmcnt(8)
	s_waitcnt lgkmcnt(0)
	s_barrier
	v_mfma_f32_16x16x32_bf16 v[102:105], v[154:157], v[190:193], v[102:105]
	v_mfma_f32_16x16x32_bf16 v[98:101], v[162:165], v[190:193], v[98:101]
	v_mfma_f32_16x16x32_bf16 v[84:87], v[154:157], v[206:209], v[84:87]
	v_mfma_f32_16x16x32_bf16 v[80:83], v[162:165], v[206:209], v[80:83]
	v_mfma_f32_16x16x32_bf16 v[68:71], v[154:157], v[218:221], v[68:71]
	v_mfma_f32_16x16x32_bf16 v[64:67], v[162:165], v[218:221], v[64:67]
	v_mfma_f32_16x16x32_bf16 v[44:47], v[154:157], v[226:229], v[44:47]
	v_mfma_f32_16x16x32_bf16 v[32:35], v[162:165], v[226:229], v[32:35]
	v_mfma_f32_16x16x32_bf16 v[102:105], v[158:161], v[202:205], v[102:105]
	v_mfma_f32_16x16x32_bf16 v[98:101], v[166:169], v[202:205], v[98:101]
	v_mfma_f32_16x16x32_bf16 v[84:87], v[158:161], v[214:217], v[84:87]
	v_mfma_f32_16x16x32_bf16 v[80:83], v[166:169], v[214:217], v[80:83]
	v_mfma_f32_16x16x32_bf16 v[68:71], v[158:161], v[222:225], v[68:71]
	v_mfma_f32_16x16x32_bf16 v[64:67], v[166:169], v[222:225], v[64:67]
	v_mfma_f32_16x16x32_bf16 v[44:47], v[158:161], v[230:233], v[44:47]
	v_mfma_f32_16x16x32_bf16 v[32:35], v[166:169], v[230:233], v[32:35]
	v_mfma_f32_16x16x32_bf16 v[60:63], v[174:177], v[190:193], v[60:63]
	v_mfma_f32_16x16x32_bf16 v[56:59], v[182:185], v[190:193], v[56:59]
	v_mfma_f32_16x16x32_bf16 v[76:79], v[174:177], v[206:209], v[76:79]
	v_mfma_f32_16x16x32_bf16 v[72:75], v[182:185], v[206:209], v[72:75]
	v_mfma_f32_16x16x32_bf16 v[52:55], v[174:177], v[218:221], v[52:55]
	v_mfma_f32_16x16x32_bf16 v[48:51], v[182:185], v[218:221], v[48:51]
	v_mfma_f32_16x16x32_bf16 v[28:31], v[174:177], v[226:229], v[28:31]
	v_mfma_f32_16x16x32_bf16 v[16:19], v[182:185], v[226:229], v[16:19]
	v_mfma_f32_16x16x32_bf16 v[60:63], v[178:181], v[202:205], v[60:63]
	v_mfma_f32_16x16x32_bf16 v[56:59], v[186:189], v[202:205], v[56:59]
	v_mfma_f32_16x16x32_bf16 v[76:79], v[178:181], v[214:217], v[76:79]
	v_mfma_f32_16x16x32_bf16 v[72:75], v[186:189], v[214:217], v[72:75]
	v_mfma_f32_16x16x32_bf16 v[52:55], v[178:181], v[222:225], v[52:55]
	v_mfma_f32_16x16x32_bf16 v[48:51], v[186:189], v[222:225], v[48:51]
	v_mfma_f32_16x16x32_bf16 v[28:31], v[178:181], v[230:233], v[28:31]
	v_mfma_f32_16x16x32_bf16 v[16:19], v[186:189], v[230:233], v[16:19]
	s_barrier
	s_setprio 0
	s_add_i32 s3, 0, 0x18000
	v_add_u32_e32 v149, s3, v144
	s_add_i32 s6, 0, 0x1c000
	ds_read_b128 v[154:157], v149
	ds_read_b128 v[158:161], v149 offset:1024
	ds_read_b128 v[162:165], v149 offset:2048
	ds_read_b128 v[166:169], v149 offset:3072
	v_add_u32_e32 v149, s6, v144
	ds_read_b128 v[174:177], v149
	ds_read_b128 v[178:181], v149 offset:1024
	ds_read_b128 v[182:185], v149 offset:2048
	ds_read_b128 v[186:189], v149 offset:3072
	s_add_u32 s44, s44, 0x160000
	s_addc_u32 s45, s45, 0
	s_mov_b32 m0, s19
	v_lshl_add_u64 v[198:199], s[44:45], 0, v[134:135]
	ds_read_b128 v[190:193], v145 offset:32768
	ds_read_b128 v[202:205], v145 offset:33792
	ds_read_b128 v[206:209], v145 offset:34816
	ds_read_b128 v[214:217], v145 offset:35840
	ds_read_b128 v[218:221], v145 offset:36864
	ds_read_b128 v[222:225], v145 offset:37888
	ds_read_b128 v[226:229], v145 offset:38912
	ds_read_b128 v[230:233], v145 offset:39936
	global_load_lds_dwordx4 v[198:199], off
	v_lshl_add_u64 v[198:199], s[44:45], 0, v[132:133]
	s_mov_b32 m0, s20
	s_nop 0
	global_load_lds_dwordx4 v[198:199], off
	s_setprio 1
	s_waitcnt vmcnt(8)
	s_waitcnt lgkmcnt(0)
	s_barrier
	v_mfma_f32_16x16x32_bf16 v[110:113], v[154:157], v[190:193], v[110:113]
	v_mfma_f32_16x16x32_bf16 v[106:109], v[162:165], v[190:193], v[106:109]
	v_mfma_f32_16x16x32_bf16 v[118:121], v[154:157], v[206:209], v[118:121]
	v_mfma_f32_16x16x32_bf16 v[114:117], v[162:165], v[206:209], v[114:117]
	v_mfma_f32_16x16x32_bf16 v[126:129], v[154:157], v[218:221], v[126:129]
	v_mfma_f32_16x16x32_bf16 v[122:125], v[162:165], v[218:221], v[122:125]
	v_mfma_f32_16x16x32_bf16 v[92:95], v[154:157], v[226:229], v[92:95]
	v_mfma_f32_16x16x32_bf16 v[88:91], v[162:165], v[226:229], v[88:91]
	v_mfma_f32_16x16x32_bf16 v[110:113], v[158:161], v[202:205], v[110:113]
	v_mfma_f32_16x16x32_bf16 v[106:109], v[166:169], v[202:205], v[106:109]
	v_mfma_f32_16x16x32_bf16 v[118:121], v[158:161], v[214:217], v[118:121]
	v_mfma_f32_16x16x32_bf16 v[114:117], v[166:169], v[214:217], v[114:117]
	v_mfma_f32_16x16x32_bf16 v[126:129], v[158:161], v[222:225], v[126:129]
	v_mfma_f32_16x16x32_bf16 v[122:125], v[166:169], v[222:225], v[122:125]
	v_mfma_f32_16x16x32_bf16 v[92:95], v[158:161], v[230:233], v[92:95]
	v_mfma_f32_16x16x32_bf16 v[88:91], v[166:169], v[230:233], v[88:91]
	v_mfma_f32_16x16x32_bf16 v[4:7], v[174:177], v[190:193], v[4:7]
	v_mfma_f32_16x16x32_bf16 v[0:3], v[182:185], v[190:193], v[0:3]
	v_mfma_f32_16x16x32_bf16 v[12:15], v[174:177], v[206:209], v[12:15]
	v_mfma_f32_16x16x32_bf16 v[8:11], v[182:185], v[206:209], v[8:11]
	v_mfma_f32_16x16x32_bf16 v[24:27], v[174:177], v[218:221], v[24:27]
	v_mfma_f32_16x16x32_bf16 v[20:23], v[182:185], v[218:221], v[20:23]
	v_mfma_f32_16x16x32_bf16 v[40:43], v[174:177], v[226:229], v[40:43]
	v_mfma_f32_16x16x32_bf16 v[36:39], v[182:185], v[226:229], v[36:39]
	v_mfma_f32_16x16x32_bf16 v[4:7], v[178:181], v[202:205], v[4:7]
	v_mfma_f32_16x16x32_bf16 v[0:3], v[186:189], v[202:205], v[0:3]
	v_mfma_f32_16x16x32_bf16 v[12:15], v[178:181], v[214:217], v[12:15]
	v_mfma_f32_16x16x32_bf16 v[8:11], v[186:189], v[214:217], v[8:11]
	v_mfma_f32_16x16x32_bf16 v[24:27], v[178:181], v[222:225], v[24:27]
	v_mfma_f32_16x16x32_bf16 v[20:23], v[186:189], v[222:225], v[20:23]
	v_mfma_f32_16x16x32_bf16 v[40:43], v[178:181], v[230:233], v[40:43]
	v_mfma_f32_16x16x32_bf16 v[36:39], v[186:189], v[230:233], v[36:39]
	s_barrier
	s_setprio 0
	s_add_i32 s3, s3, s5
	v_lshl_add_u64 v[146:147], v[146:147], 0, s[30:31]
	s_mov_b32 m0, s3
	ds_read_b128 v[190:193], v145 offset:49152
	ds_read_b128 v[202:205], v145 offset:50176
	ds_read_b128 v[206:209], v145 offset:51200
	ds_read_b128 v[214:217], v145 offset:52224
	ds_read_b128 v[218:221], v145 offset:53248
	ds_read_b128 v[222:225], v145 offset:54272
	ds_read_b128 v[226:229], v145 offset:55296
	ds_read_b128 v[230:233], v145 offset:56320
	global_load_lds_dwordx4 v[146:147], off
	s_add_i32 m0, s3, 0x2000
	s_add_u32 s42, s42, 0x160080
	v_lshl_add_u64 v[146:147], v[150:151], 0, s[30:31]
	s_addc_u32 s43, s43, 0
	s_add_i32 s3, s6, s5
	global_load_lds_dwordx4 v[146:147], off
	v_lshl_add_u64 v[146:147], s[42:43], 0, v[96:97]
	s_mov_b32 m0, s3
	s_nop 0
	global_load_lds_dwordx4 v[146:147], off
	v_lshl_add_u64 v[146:147], s[42:43], 0, v[130:131]
	s_add_i32 m0, s3, 0x2000
	s_nop 0
	global_load_lds_dwordx4 v[146:147], off
	v_lshl_add_u64 v[146:147], v[170:171], 0, s[30:31]
	s_mov_b32 m0, s37
	s_nop 0
	global_load_lds_dwordx4 v[146:147], off
	v_lshl_add_u64 v[146:147], v[194:195], 0, s[30:31]
	s_mov_b32 m0, s52
	s_nop 0
	global_load_lds_dwordx4 v[146:147], off
	s_setprio 1
	s_waitcnt vmcnt(8)
	s_waitcnt lgkmcnt(0)
	s_barrier
	v_mfma_f32_16x16x32_bf16 v[102:105], v[154:157], v[190:193], v[102:105]
	v_mfma_f32_16x16x32_bf16 v[98:101], v[162:165], v[190:193], v[98:101]
	v_mfma_f32_16x16x32_bf16 v[84:87], v[154:157], v[206:209], v[84:87]
	v_mfma_f32_16x16x32_bf16 v[80:83], v[162:165], v[206:209], v[80:83]
	v_mfma_f32_16x16x32_bf16 v[68:71], v[154:157], v[218:221], v[68:71]
	v_mfma_f32_16x16x32_bf16 v[64:67], v[162:165], v[218:221], v[64:67]
	v_mfma_f32_16x16x32_bf16 v[44:47], v[154:157], v[226:229], v[44:47]
	v_mfma_f32_16x16x32_bf16 v[32:35], v[162:165], v[226:229], v[32:35]
	v_mfma_f32_16x16x32_bf16 v[102:105], v[158:161], v[202:205], v[102:105]
	v_mfma_f32_16x16x32_bf16 v[98:101], v[166:169], v[202:205], v[98:101]
	v_mfma_f32_16x16x32_bf16 v[84:87], v[158:161], v[214:217], v[84:87]
	v_mfma_f32_16x16x32_bf16 v[80:83], v[166:169], v[214:217], v[80:83]
	v_mfma_f32_16x16x32_bf16 v[68:71], v[158:161], v[222:225], v[68:71]
	v_mfma_f32_16x16x32_bf16 v[64:67], v[166:169], v[222:225], v[64:67]
	v_mfma_f32_16x16x32_bf16 v[44:47], v[158:161], v[230:233], v[44:47]
	v_mfma_f32_16x16x32_bf16 v[32:35], v[166:169], v[230:233], v[32:35]
	v_mfma_f32_16x16x32_bf16 v[60:63], v[174:177], v[190:193], v[60:63]
	v_mfma_f32_16x16x32_bf16 v[56:59], v[182:185], v[190:193], v[56:59]
	v_mfma_f32_16x16x32_bf16 v[76:79], v[174:177], v[206:209], v[76:79]
	v_mfma_f32_16x16x32_bf16 v[72:75], v[182:185], v[206:209], v[72:75]
	v_mfma_f32_16x16x32_bf16 v[52:55], v[174:177], v[218:221], v[52:55]
	v_mfma_f32_16x16x32_bf16 v[48:51], v[182:185], v[218:221], v[48:51]
	v_mfma_f32_16x16x32_bf16 v[28:31], v[174:177], v[226:229], v[28:31]
	v_mfma_f32_16x16x32_bf16 v[16:19], v[182:185], v[226:229], v[16:19]
	v_mfma_f32_16x16x32_bf16 v[60:63], v[178:181], v[202:205], v[60:63]
	v_mfma_f32_16x16x32_bf16 v[56:59], v[186:189], v[202:205], v[56:59]
	v_mfma_f32_16x16x32_bf16 v[76:79], v[178:181], v[214:217], v[76:79]
	v_mfma_f32_16x16x32_bf16 v[72:75], v[186:189], v[214:217], v[72:75]
	v_mfma_f32_16x16x32_bf16 v[52:55], v[178:181], v[222:225], v[52:55]
	v_mfma_f32_16x16x32_bf16 v[48:51], v[186:189], v[222:225], v[48:51]
	v_mfma_f32_16x16x32_bf16 v[28:31], v[178:181], v[230:233], v[28:31]
	v_mfma_f32_16x16x32_bf16 v[16:19], v[186:189], v[230:233], v[16:19]
	s_barrier
	s_setprio 0
	s_add_i32 s2, s2, 2
	s_add_u32 s34, s34, 0x100
	s_addc_u32 s35, s35, 0
	s_cmpk_gt_u32 s2, 0x55
	s_cbranch_scc0 .LBB0_1357
	s_nop 0
	s_nop 0
	s_nop 0
	s_nop 0
	s_nop 0
	s_nop 0
	s_nop 0
	s_nop 0
	s_nop 0
	s_nop 0
	s_nop 0
	s_nop 0
	s_and_b64 vcc, exec, s[12:13]
	s_cbranch_vccz .LBB0_1360
	s_barrier

.LBB0_1413:
	s_add_u32 s24, s22, 0x100
	s_addc_u32 s25, s23, 0
	s_add_i32 s45, 0, 0x10000
	s_cmpk_eq_i32 s6, 0x54
	s_cselect_b32 s39, s13, s25
	s_cselect_b32 s38, s12, s24
	s_cselect_b32 s35, s15, s3
	s_cselect_b32 s34, s14, s2
	s_add_i32 s46, 0, 0x14000
	v_add_u32_e32 v142, s45, v155
	v_add_u32_e32 v152, s46, v155
	ds_read_b128 v[130:133], v142
	ds_read_b128 v[134:137], v142 offset:1024
	ds_read_b128 v[138:141], v142 offset:2048
	ds_read_b128 v[142:145], v142 offset:3072
	ds_read_b128 v[158:161], v152
	ds_read_b128 v[162:165], v152 offset:1024
	ds_read_b128 v[166:169], v152 offset:2048
	ds_read_b128 v[170:173], v152 offset:3072
	v_lshl_add_u64 v[152:153], s[22:23], 0, v[148:149]
	s_add_i32 m0, s5, 0xc000
	ds_read_b128 v[174:177], v157
	ds_read_b128 v[178:181], v157 offset:1024
	ds_read_b128 v[182:185], v157 offset:2048
	ds_read_b128 v[186:189], v157 offset:3072
	ds_read_b128 v[190:193], v157 offset:4096
	ds_read_b128 v[202:205], v157 offset:5120
	ds_read_b128 v[206:209], v157 offset:6144
	ds_read_b128 v[214:217], v157 offset:7168
	global_load_lds_dwordx4 v[152:153], off
	v_lshl_add_u64 v[152:153], s[22:23], 0, v[150:151]
	s_add_i32 m0, s5, 0xe000
	s_nop 0
	global_load_lds_dwordx4 v[152:153], off
	s_setprio 1
	s_waitcnt vmcnt(8)
	s_waitcnt lgkmcnt(0)
	s_barrier
	v_mfma_f32_16x16x32_bf16 v[126:129], v[130:133], v[174:177], v[126:129]
	v_mfma_f32_16x16x32_bf16 v[122:125], v[138:141], v[174:177], v[122:125]
	v_mfma_f32_16x16x32_bf16 v[114:117], v[130:133], v[182:185], v[114:117]
	v_mfma_f32_16x16x32_bf16 v[110:113], v[138:141], v[182:185], v[110:113]
	v_mfma_f32_16x16x32_bf16 v[98:101], v[130:133], v[190:193], v[98:101]
	v_mfma_f32_16x16x32_bf16 v[92:95], v[138:141], v[190:193], v[92:95]
	v_mfma_f32_16x16x32_bf16 v[80:83], v[130:133], v[206:209], v[80:83]
	v_mfma_f32_16x16x32_bf16 v[76:79], v[138:141], v[206:209], v[76:79]
	v_mfma_f32_16x16x32_bf16 v[126:129], v[134:137], v[178:181], v[126:129]
	v_mfma_f32_16x16x32_bf16 v[122:125], v[142:145], v[178:181], v[122:125]
	v_mfma_f32_16x16x32_bf16 v[114:117], v[134:137], v[186:189], v[114:117]
	v_mfma_f32_16x16x32_bf16 v[110:113], v[142:145], v[186:189], v[110:113]
	v_mfma_f32_16x16x32_bf16 v[98:101], v[134:137], v[202:205], v[98:101]
	v_mfma_f32_16x16x32_bf16 v[92:95], v[142:145], v[202:205], v[92:95]
	v_mfma_f32_16x16x32_bf16 v[80:83], v[134:137], v[214:217], v[80:83]
	v_mfma_f32_16x16x32_bf16 v[76:79], v[142:145], v[214:217], v[76:79]
	v_mfma_f32_16x16x32_bf16 v[118:121], v[158:161], v[174:177], v[118:121]
	v_mfma_f32_16x16x32_bf16 v[106:109], v[166:169], v[174:177], v[106:109]
	v_mfma_f32_16x16x32_bf16 v[102:105], v[158:161], v[182:185], v[102:105]
	v_mfma_f32_16x16x32_bf16 v[88:91], v[166:169], v[182:185], v[88:91]
	v_mfma_f32_16x16x32_bf16 v[84:87], v[158:161], v[190:193], v[84:87]
	v_mfma_f32_16x16x32_bf16 v[72:75], v[166:169], v[190:193], v[72:75]
	v_mfma_f32_16x16x32_bf16 v[68:71], v[158:161], v[206:209], v[68:71]
	v_mfma_f32_16x16x32_bf16 v[64:67], v[166:169], v[206:209], v[64:67]
	v_mfma_f32_16x16x32_bf16 v[118:121], v[162:165], v[178:181], v[118:121]
	v_mfma_f32_16x16x32_bf16 v[106:109], v[170:173], v[178:181], v[106:109]
	v_mfma_f32_16x16x32_bf16 v[102:105], v[162:165], v[186:189], v[102:105]
	v_mfma_f32_16x16x32_bf16 v[88:91], v[170:173], v[186:189], v[88:91]
	v_mfma_f32_16x16x32_bf16 v[84:87], v[162:165], v[202:205], v[84:87]
	v_mfma_f32_16x16x32_bf16 v[72:75], v[170:173], v[202:205], v[72:75]
	v_mfma_f32_16x16x32_bf16 v[68:71], v[162:165], v[214:217], v[68:71]
	v_mfma_f32_16x16x32_bf16 v[64:67], v[170:173], v[214:217], v[64:67]
	s_barrier
	s_setprio 0
	s_add_i32 s22, s45, s4
	v_lshl_add_u64 v[152:153], s[34:35], 0, v[96:97]
	s_mov_b32 m0, s22
	ds_read_b128 v[174:177], v157 offset:16384
	ds_read_b128 v[178:181], v157 offset:17408
	ds_read_b128 v[182:185], v157 offset:18432
	ds_read_b128 v[186:189], v157 offset:19456
	ds_read_b128 v[190:193], v157 offset:20480
	ds_read_b128 v[202:205], v157 offset:21504
	ds_read_b128 v[206:209], v157 offset:22528
	ds_read_b128 v[214:217], v157 offset:23552
	global_load_lds_dwordx4 v[152:153], off
	s_add_i32 m0, s22, 0x2000
	s_add_u32 s22, s34, 0x160000
	v_lshl_add_u64 v[194:195], s[34:35], 0, v[146:147]
	s_addc_u32 s23, s35, 0
	s_add_i32 s45, s46, s4
	global_load_lds_dwordx4 v[194:195], off
	v_lshl_add_u64 v[198:199], s[22:23], 0, v[96:97]
	s_mov_b32 m0, s45
	v_lshl_add_u64 v[200:201], s[38:39], 0, v[146:147]
	global_load_lds_dwordx4 v[198:199], off
	v_lshl_add_u64 v[198:199], s[22:23], 0, v[146:147]
	s_add_i32 m0, s45, 0x2000
	s_nop 0
	global_load_lds_dwordx4 v[198:199], off
	v_lshl_add_u64 v[198:199], s[38:39], 0, v[96:97]
	s_mov_b32 m0, s5
	s_nop 0
	global_load_lds_dwordx4 v[198:199], off
	s_mov_b32 m0, s17
	s_nop 0
	global_load_lds_dwordx4 v[200:201], off
	s_setprio 1
	s_waitcnt vmcnt(8)
	s_waitcnt lgkmcnt(0)
	s_barrier
	v_mfma_f32_16x16x32_bf16 v[60:63], v[130:133], v[174:177], v[60:63]
	v_mfma_f32_16x16x32_bf16 v[56:59], v[138:141], v[174:177], v[56:59]
	v_mfma_f32_16x16x32_bf16 v[48:51], v[130:133], v[182:185], v[48:51]
	v_mfma_f32_16x16x32_bf16 v[44:47], v[138:141], v[182:185], v[44:47]
	v_mfma_f32_16x16x32_bf16 v[32:35], v[130:133], v[190:193], v[32:35]
	v_mfma_f32_16x16x32_bf16 v[28:31], v[138:141], v[190:193], v[28:31]
	v_mfma_f32_16x16x32_bf16 v[16:19], v[130:133], v[206:209], v[16:19]
	v_mfma_f32_16x16x32_bf16 v[12:15], v[138:141], v[206:209], v[12:15]
	v_mfma_f32_16x16x32_bf16 v[60:63], v[134:137], v[178:181], v[60:63]
	v_mfma_f32_16x16x32_bf16 v[56:59], v[142:145], v[178:181], v[56:59]
	v_mfma_f32_16x16x32_bf16 v[48:51], v[134:137], v[186:189], v[48:51]
	v_mfma_f32_16x16x32_bf16 v[44:47], v[142:145], v[186:189], v[44:47]
	v_mfma_f32_16x16x32_bf16 v[32:35], v[134:137], v[202:205], v[32:35]
	v_mfma_f32_16x16x32_bf16 v[28:31], v[142:145], v[202:205], v[28:31]
	v_mfma_f32_16x16x32_bf16 v[16:19], v[134:137], v[214:217], v[16:19]
	v_mfma_f32_16x16x32_bf16 v[12:15], v[142:145], v[214:217], v[12:15]
	v_mfma_f32_16x16x32_bf16 v[52:55], v[158:161], v[174:177], v[52:55]
	v_mfma_f32_16x16x32_bf16 v[40:43], v[166:169], v[174:177], v[40:43]
	v_mfma_f32_16x16x32_bf16 v[36:39], v[158:161], v[182:185], v[36:39]
	v_mfma_f32_16x16x32_bf16 v[24:27], v[166:169], v[182:185], v[24:27]
	v_mfma_f32_16x16x32_bf16 v[20:23], v[158:161], v[190:193], v[20:23]
	v_mfma_f32_16x16x32_bf16 v[8:11], v[166:169], v[190:193], v[8:11]
	v_mfma_f32_16x16x32_bf16 v[4:7], v[158:161], v[206:209], v[4:7]
	v_mfma_f32_16x16x32_bf16 v[0:3], v[166:169], v[206:209], v[0:3]
	v_mfma_f32_16x16x32_bf16 v[52:55], v[162:165], v[178:181], v[52:55]
	v_mfma_f32_16x16x32_bf16 v[40:43], v[170:173], v[178:181], v[40:43]
	v_mfma_f32_16x16x32_bf16 v[36:39], v[162:165], v[186:189], v[36:39]
	v_mfma_f32_16x16x32_bf16 v[24:27], v[170:173], v[186:189], v[24:27]
	v_mfma_f32_16x16x32_bf16 v[20:23], v[162:165], v[202:205], v[20:23]
	v_mfma_f32_16x16x32_bf16 v[8:11], v[170:173], v[202:205], v[8:11]
	v_mfma_f32_16x16x32_bf16 v[4:7], v[162:165], v[214:217], v[4:7]
	v_mfma_f32_16x16x32_bf16 v[0:3], v[170:173], v[214:217], v[0:3]
	s_barrier
	s_setprio 0
	s_add_i32 s45, 0, 0x18000
	s_add_i32 s46, 0, 0x1c000
	v_add_u32_e32 v142, s45, v155
	v_add_u32_e32 v170, s46, v155
	ds_read_b128 v[130:133], v142
	ds_read_b128 v[134:137], v142 offset:1024
	ds_read_b128 v[138:141], v142 offset:2048
	ds_read_b128 v[142:145], v142 offset:3072
	ds_read_b128 v[158:161], v170
	ds_read_b128 v[162:165], v170 offset:1024
	ds_read_b128 v[166:169], v170 offset:2048
	ds_read_b128 v[170:173], v170 offset:3072
	s_add_u32 s22, s38, 0x160000
	s_addc_u32 s23, s39, 0
	s_mov_b32 m0, s18
	v_lshl_add_u64 v[218:219], s[22:23], 0, v[96:97]
	ds_read_b128 v[174:177], v157 offset:32768
	ds_read_b128 v[178:181], v157 offset:33792
	ds_read_b128 v[182:185], v157 offset:34816
	ds_read_b128 v[186:189], v157 offset:35840
	ds_read_b128 v[190:193], v157 offset:36864
	ds_read_b128 v[202:205], v157 offset:37888
	ds_read_b128 v[206:209], v157 offset:38912
	ds_read_b128 v[214:217], v157 offset:39936
	global_load_lds_dwordx4 v[218:219], off
	v_lshl_add_u64 v[218:219], s[22:23], 0, v[146:147]
	s_mov_b32 m0, s19
	s_nop 0
	global_load_lds_dwordx4 v[218:219], off
	s_setprio 1
	s_waitcnt vmcnt(8)
	s_waitcnt lgkmcnt(0)
	s_barrier
	v_mfma_f32_16x16x32_bf16 v[126:129], v[130:133], v[174:177], v[126:129]
	v_mfma_f32_16x16x32_bf16 v[122:125], v[138:141], v[174:177], v[122:125]
	v_mfma_f32_16x16x32_bf16 v[114:117], v[130:133], v[182:185], v[114:117]
	v_mfma_f32_16x16x32_bf16 v[110:113], v[138:141], v[182:185], v[110:113]
	v_mfma_f32_16x16x32_bf16 v[98:101], v[130:133], v[190:193], v[98:101]
	v_mfma_f32_16x16x32_bf16 v[92:95], v[138:141], v[190:193], v[92:95]
	v_mfma_f32_16x16x32_bf16 v[80:83], v[130:133], v[206:209], v[80:83]
	v_mfma_f32_16x16x32_bf16 v[76:79], v[138:141], v[206:209], v[76:79]
	v_mfma_f32_16x16x32_bf16 v[126:129], v[134:137], v[178:181], v[126:129]
	v_mfma_f32_16x16x32_bf16 v[122:125], v[142:145], v[178:181], v[122:125]
	v_mfma_f32_16x16x32_bf16 v[114:117], v[134:137], v[186:189], v[114:117]
	v_mfma_f32_16x16x32_bf16 v[110:113], v[142:145], v[186:189], v[110:113]
	v_mfma_f32_16x16x32_bf16 v[98:101], v[134:137], v[202:205], v[98:101]
	v_mfma_f32_16x16x32_bf16 v[92:95], v[142:145], v[202:205], v[92:95]
	v_mfma_f32_16x16x32_bf16 v[80:83], v[134:137], v[214:217], v[80:83]
	v_mfma_f32_16x16x32_bf16 v[76:79], v[142:145], v[214:217], v[76:79]
	v_mfma_f32_16x16x32_bf16 v[118:121], v[158:161], v[174:177], v[118:121]
	v_mfma_f32_16x16x32_bf16 v[106:109], v[166:169], v[174:177], v[106:109]
	v_mfma_f32_16x16x32_bf16 v[102:105], v[158:161], v[182:185], v[102:105]
	v_mfma_f32_16x16x32_bf16 v[88:91], v[166:169], v[182:185], v[88:91]
	v_mfma_f32_16x16x32_bf16 v[84:87], v[158:161], v[190:193], v[84:87]
	v_mfma_f32_16x16x32_bf16 v[72:75], v[166:169], v[190:193], v[72:75]
	v_mfma_f32_16x16x32_bf16 v[68:71], v[158:161], v[206:209], v[68:71]
	v_mfma_f32_16x16x32_bf16 v[64:67], v[166:169], v[206:209], v[64:67]
	v_mfma_f32_16x16x32_bf16 v[118:121], v[162:165], v[178:181], v[118:121]
	v_mfma_f32_16x16x32_bf16 v[106:109], v[170:173], v[178:181], v[106:109]
	v_mfma_f32_16x16x32_bf16 v[102:105], v[162:165], v[186:189], v[102:105]
	v_mfma_f32_16x16x32_bf16 v[88:91], v[170:173], v[186:189], v[88:91]
	v_mfma_f32_16x16x32_bf16 v[84:87], v[162:165], v[202:205], v[84:87]
	v_mfma_f32_16x16x32_bf16 v[72:75], v[170:173], v[202:205], v[72:75]
	v_mfma_f32_16x16x32_bf16 v[68:71], v[162:165], v[214:217], v[68:71]
	v_mfma_f32_16x16x32_bf16 v[64:67], v[170:173], v[214:217], v[64:67]
	s_barrier
	s_setprio 0
	s_add_i32 s22, s45, s4
	v_lshl_add_u64 v[152:153], v[152:153], 0, s[30:31]
	s_mov_b32 m0, s22
	ds_read_b128 v[174:177], v157 offset:49152
	ds_read_b128 v[178:181], v157 offset:50176
	ds_read_b128 v[182:185], v157 offset:51200
	ds_read_b128 v[186:189], v157 offset:52224
	ds_read_b128 v[190:193], v157 offset:53248
	ds_read_b128 v[202:205], v157 offset:54272
	ds_read_b128 v[206:209], v157 offset:55296
	ds_read_b128 v[214:217], v157 offset:56320
	global_load_lds_dwordx4 v[152:153], off
	s_add_i32 m0, s22, 0x2000
	s_add_u32 s22, s34, 0x160080
	v_lshl_add_u64 v[152:153], v[194:195], 0, s[30:31]
	s_addc_u32 s23, s35, 0
	s_add_i32 s34, s46, s4
	global_load_lds_dwordx4 v[152:153], off
	v_lshl_add_u64 v[152:153], s[22:23], 0, v[96:97]
	s_mov_b32 m0, s34
	s_nop 0
	global_load_lds_dwordx4 v[152:153], off
	v_lshl_add_u64 v[152:153], s[22:23], 0, v[146:147]
	s_add_i32 m0, s34, 0x2000
	s_nop 0
	global_load_lds_dwordx4 v[152:153], off
	v_lshl_add_u64 v[152:153], v[198:199], 0, s[30:31]
	s_mov_b32 m0, s20
	s_nop 0
	global_load_lds_dwordx4 v[152:153], off
	v_lshl_add_u64 v[152:153], v[200:201], 0, s[30:31]
	s_mov_b32 m0, s36
	s_nop 0
	global_load_lds_dwordx4 v[152:153], off
	s_setprio 1
	s_waitcnt vmcnt(8)
	s_waitcnt lgkmcnt(0)
	s_barrier
	v_mfma_f32_16x16x32_bf16 v[60:63], v[130:133], v[174:177], v[60:63]
	v_mfma_f32_16x16x32_bf16 v[56:59], v[138:141], v[174:177], v[56:59]
	v_mfma_f32_16x16x32_bf16 v[48:51], v[130:133], v[182:185], v[48:51]
	v_mfma_f32_16x16x32_bf16 v[44:47], v[138:141], v[182:185], v[44:47]
	v_mfma_f32_16x16x32_bf16 v[32:35], v[130:133], v[190:193], v[32:35]
	v_mfma_f32_16x16x32_bf16 v[28:31], v[138:141], v[190:193], v[28:31]
	v_mfma_f32_16x16x32_bf16 v[16:19], v[130:133], v[206:209], v[16:19]
	v_mfma_f32_16x16x32_bf16 v[12:15], v[138:141], v[206:209], v[12:15]
	v_mfma_f32_16x16x32_bf16 v[60:63], v[134:137], v[178:181], v[60:63]
	v_mfma_f32_16x16x32_bf16 v[56:59], v[142:145], v[178:181], v[56:59]
	v_mfma_f32_16x16x32_bf16 v[48:51], v[134:137], v[186:189], v[48:51]
	v_mfma_f32_16x16x32_bf16 v[44:47], v[142:145], v[186:189], v[44:47]
	v_mfma_f32_16x16x32_bf16 v[32:35], v[134:137], v[202:205], v[32:35]
	v_mfma_f32_16x16x32_bf16 v[28:31], v[142:145], v[202:205], v[28:31]
	v_mfma_f32_16x16x32_bf16 v[16:19], v[134:137], v[214:217], v[16:19]
	v_mfma_f32_16x16x32_bf16 v[12:15], v[142:145], v[214:217], v[12:15]
	v_mfma_f32_16x16x32_bf16 v[52:55], v[158:161], v[174:177], v[52:55]
	v_mfma_f32_16x16x32_bf16 v[40:43], v[166:169], v[174:177], v[40:43]
	v_mfma_f32_16x16x32_bf16 v[36:39], v[158:161], v[182:185], v[36:39]
	v_mfma_f32_16x16x32_bf16 v[24:27], v[166:169], v[182:185], v[24:27]
	v_mfma_f32_16x16x32_bf16 v[20:23], v[158:161], v[190:193], v[20:23]
	v_mfma_f32_16x16x32_bf16 v[8:11], v[166:169], v[190:193], v[8:11]
	v_mfma_f32_16x16x32_bf16 v[4:7], v[158:161], v[206:209], v[4:7]
	v_mfma_f32_16x16x32_bf16 v[0:3], v[166:169], v[206:209], v[0:3]
	v_mfma_f32_16x16x32_bf16 v[52:55], v[162:165], v[178:181], v[52:55]
	v_mfma_f32_16x16x32_bf16 v[40:43], v[170:173], v[178:181], v[40:43]
	v_mfma_f32_16x16x32_bf16 v[36:39], v[162:165], v[186:189], v[36:39]
	v_mfma_f32_16x16x32_bf16 v[24:27], v[170:173], v[186:189], v[24:27]
	v_mfma_f32_16x16x32_bf16 v[20:23], v[162:165], v[202:205], v[20:23]
	v_mfma_f32_16x16x32_bf16 v[8:11], v[170:173], v[202:205], v[8:11]
	v_mfma_f32_16x16x32_bf16 v[4:7], v[162:165], v[214:217], v[4:7]
	v_mfma_f32_16x16x32_bf16 v[0:3], v[170:173], v[214:217], v[0:3]
	s_barrier
	s_setprio 0
	s_add_i32 s6, s6, 2
	s_add_u32 s2, s2, 0x100
	s_addc_u32 s3, s3, 0
	s_cmpk_gt_u32 s6, 0x55
	s_mov_b64 s[22:23], s[24:25]
	s_cbranch_scc0 .LBB0_1413
	s_nop 0
	s_nop 0
	s_nop 0
	s_nop 0
	s_nop 0
	s_nop 0
	s_nop 0
	s_nop 0
	s_nop 0
	s_nop 0
	s_nop 0
	s_nop 0
	s_and_b64 vcc, exec, s[10:11]
	s_cbranch_vccz .LBB0_1416
	s_barrier
